# MFMA order inside each 16-MFMA sub-block: both k-steps of an accumulator back to back (accumulator-chain forwarding), on top of v49 (the previous measurement v54 was by mistake a diagnostic file with
# speedup vs baseline: 1.0131x; 1.0079x over previous
; #define PG8_STAGE(bufoff, gbase, voff) do { _Pragma("unroll") for (int _i = 0; _i < 2; ++_i) \
;         __builtin_amdgcn_global_load_lds((const unsigned*)((const char*)(gbase) + (voff)[_i]), (PG8_LAS unsigned*)(lds + (bufoff) + ldsw + _i * 8192), 16, 0, 0); } while (0)
; #define PG8_LDA(dst, b, h) do { _Pragma("unroll") for (int m = 0; m < 4; ++m) _Pragma("unroll") for (int k = 0; k < 2; ++k) dst[m][k] = *(const PG8_LAS bf16x8*)(lds + PG8_SA(b, h) + aoff + m * 2048 + k * 1024); } while (0)
; #define PG8_LDB(dst, b, h) do { _Pragma("unroll") for (int n = 0; n < 2; ++n) _Pragma("unroll") for (int k = 0; k < 2; ++k) dst[n][k] = *(const PG8_LAS bf16x8*)(lds + PG8_SB(b, h) + boff + n * 2048 + k * 1024); } while (0)
; #define PG8_WAIT_L(n) asm volatile("s_waitcnt lgkmcnt(" #n ")" ::: "memory")
; #define PG8_WAIT_V_SEL(sel) asm volatile("s_cmp_eq_u32 %0, 0\n\ts_cbranch_scc1 .Lw8_%=\n\ts_waitcnt vmcnt(22)\n\ts_branch .Lwd_%=\n.Lw8_%=:\n\ts_waitcnt vmcnt(8)\n.Lwd_%=:" :: "s"(sel) : "memory", "scc")
; #define PG8_BAR __builtin_amdgcn_s_barrier()
; #define PG8_SCHED __builtin_amdgcn_sched_barrier(0)
;     ...
;             PG8_LDB(B0, 0, 0); PG8_LDB(B1, 0, 1); PG8_SCHED; PG8_LDA(At, 0, 0); PG8_STAGE(PG8_SA(1, 1), a1 + hstep, voffA);
;             PG8_WAIT_V_SEL(relax);
;             PG8_WAIT_L(0); PG8_BAR; PG8_MMA(0, 0, At, B0); PG8_MMA(0, 1, At, B1); PG8_BAR; PG8_SCHED;
;             PG8_LDA(At, 0, 1); PG8_STAGE(PG8_SB(0, 0), b2, voffB); PG8_STAGE(PG8_SB(0, 1), b2 + hstep, voffB); PG8_STAGE(PG8_SA(0, 0), a2, voffA);
;             PG8_WAIT_V_SEL(relax);
;             PG8_WAIT_L(0); PG8_BAR; PG8_MMA(1, 0, At, B0); PG8_MMA(1, 1, At, B1); PG8_BAR; PG8_SCHED;
.LBB0_234:
	s_add_u32 s0, s78, 0xfff80080
	s_addc_u32 s1, s79, -1
	s_add_i32 s40, 0, 0x10000
	s_cmp_eq_u32 s37, 28
	s_cselect_b32 s83, s19, s1
	s_cselect_b32 s82, s20, s0
	s_cselect_b32 s81, s24, s35
	s_cselect_b32 s80, s31, s33
	s_add_i32 s41, 0, 0x14000
	ds_read_b128 v[142:145], v168
	ds_read_b128 v[146:149], v168 offset:1024
	ds_read_b128 v[150:153], v168 offset:2048
	ds_read_b128 v[154:157], v168 offset:3072
	ds_read_b128 v[158:161], v168 offset:16384
	ds_read_b128 v[162:165], v168 offset:17408
	ds_read_b128 v[174:177], v168 offset:18432
	ds_read_b128 v[188:191], v168 offset:19456
	s_add_i32 m0, s75, 0xc000
	ds_read_b128 v[198:201], v196
	ds_read_b128 v[202:205], v196 offset:1024
	ds_read_b128 v[206:209], v196 offset:2048
	ds_read_b128 v[210:213], v196 offset:3072
	ds_read_b128 v[214:217], v196 offset:4096
	ds_read_b128 v[218:221], v196 offset:5120
	ds_read_b128 v[222:225], v196 offset:6144
	ds_read_b128 v[226:229], v196 offset:7168
	global_load_lds_dwordx4 v138, s[78:79]
	s_add_i32 m0, s75, 0xe000
	s_nop 0
	global_load_lds_dwordx4 v140, s[78:79]
	s_waitcnt vmcnt(8)
	s_waitcnt lgkmcnt(0)
	s_setprio 1
	s_barrier
	v_mfma_f32_16x16x32_bf16 v[126:129], v[142:145], v[198:201], v[126:129]
	v_mfma_f32_16x16x32_bf16 v[126:129], v[146:149], v[202:205], v[126:129]
	v_mfma_f32_16x16x32_bf16 v[110:113], v[150:153], v[198:201], v[110:113]
	v_mfma_f32_16x16x32_bf16 v[110:113], v[154:157], v[202:205], v[110:113]
	v_mfma_f32_16x16x32_bf16 v[122:125], v[142:145], v[206:209], v[122:125]
	v_mfma_f32_16x16x32_bf16 v[122:125], v[146:149], v[210:213], v[122:125]
	v_mfma_f32_16x16x32_bf16 v[106:109], v[150:153], v[206:209], v[106:109]
	v_mfma_f32_16x16x32_bf16 v[106:109], v[154:157], v[210:213], v[106:109]
	v_mfma_f32_16x16x32_bf16 v[118:121], v[142:145], v[214:217], v[118:121]
	v_mfma_f32_16x16x32_bf16 v[118:121], v[146:149], v[218:221], v[118:121]
	v_mfma_f32_16x16x32_bf16 v[102:105], v[150:153], v[214:217], v[102:105]
	v_mfma_f32_16x16x32_bf16 v[102:105], v[154:157], v[218:221], v[102:105]
	v_mfma_f32_16x16x32_bf16 v[114:117], v[142:145], v[222:225], v[114:117]
	v_mfma_f32_16x16x32_bf16 v[114:117], v[146:149], v[226:229], v[114:117]
	v_mfma_f32_16x16x32_bf16 v[98:101], v[150:153], v[222:225], v[98:101]
	v_mfma_f32_16x16x32_bf16 v[98:101], v[154:157], v[226:229], v[98:101]
	v_mfma_f32_16x16x32_bf16 v[82:85], v[158:161], v[198:201], v[82:85]
	v_mfma_f32_16x16x32_bf16 v[82:85], v[162:165], v[202:205], v[82:85]
	v_mfma_f32_16x16x32_bf16 v[30:33], v[174:177], v[198:201], v[30:33]
	v_mfma_f32_16x16x32_bf16 v[30:33], v[188:191], v[202:205], v[30:33]
	v_mfma_f32_16x16x32_bf16 v[70:73], v[158:161], v[206:209], v[70:73]
	v_mfma_f32_16x16x32_bf16 v[70:73], v[162:165], v[210:213], v[70:73]
	v_mfma_f32_16x16x32_bf16 v[26:29], v[174:177], v[206:209], v[26:29]
	v_mfma_f32_16x16x32_bf16 v[26:29], v[188:191], v[210:213], v[26:29]
	v_mfma_f32_16x16x32_bf16 v[66:69], v[158:161], v[214:217], v[66:69]
	v_mfma_f32_16x16x32_bf16 v[66:69], v[162:165], v[218:221], v[66:69]
	v_mfma_f32_16x16x32_bf16 v[22:25], v[174:177], v[214:217], v[22:25]
	v_mfma_f32_16x16x32_bf16 v[22:25], v[188:191], v[218:221], v[22:25]
	v_mfma_f32_16x16x32_bf16 v[58:61], v[158:161], v[222:225], v[58:61]
	v_mfma_f32_16x16x32_bf16 v[58:61], v[162:165], v[226:229], v[58:61]
	v_mfma_f32_16x16x32_bf16 v[18:21], v[174:177], v[222:225], v[18:21]
	v_mfma_f32_16x16x32_bf16 v[18:21], v[188:191], v[226:229], v[18:21]
	s_barrier
	s_setprio 0
	s_add_i32 s0, s40, s87
	s_mov_b32 m0, s0
	ds_read_b128 v[198:201], v196 offset:16384
	ds_read_b128 v[202:205], v196 offset:17408
	ds_read_b128 v[206:209], v196 offset:18432
	ds_read_b128 v[210:213], v196 offset:19456
	ds_read_b128 v[214:217], v196 offset:20480
	ds_read_b128 v[218:221], v196 offset:21504
	ds_read_b128 v[222:225], v196 offset:22528
	ds_read_b128 v[226:229], v196 offset:23552
	global_load_lds_dwordx4 v182, s[80:81]
	s_add_i32 m0, s0, 0x2000
	s_add_u32 s0, s80, 0x80000
	s_addc_u32 s1, s81, 0
	s_add_i32 s40, s41, s87
	global_load_lds_dwordx4 v134, s[80:81]
	s_mov_b32 m0, s40
	s_nop 0
	global_load_lds_dwordx4 v182, s[0:1]
	s_add_i32 m0, s40, 0x2000
	s_nop 0
	global_load_lds_dwordx4 v134, s[0:1]
	s_mov_b32 m0, s75
	s_nop 0
	global_load_lds_dwordx4 v130, s[82:83]
	s_mov_b32 m0, s88
	s_nop 0
	global_load_lds_dwordx4 v132, s[82:83]
	s_waitcnt vmcnt(8)
	s_waitcnt lgkmcnt(0)
	s_setprio 1
	s_barrier
	v_mfma_f32_16x16x32_bf16 v[94:97], v[142:145], v[198:201], v[94:97]
	v_mfma_f32_16x16x32_bf16 v[94:97], v[146:149], v[202:205], v[94:97]
	v_mfma_f32_16x16x32_bf16 v[74:77], v[150:153], v[198:201], v[74:77]
	v_mfma_f32_16x16x32_bf16 v[74:77], v[154:157], v[202:205], v[74:77]
	v_mfma_f32_16x16x32_bf16 v[90:93], v[142:145], v[206:209], v[90:93]
	v_mfma_f32_16x16x32_bf16 v[90:93], v[146:149], v[210:213], v[90:93]
	v_mfma_f32_16x16x32_bf16 v[62:65], v[150:153], v[206:209], v[62:65]
	v_mfma_f32_16x16x32_bf16 v[62:65], v[154:157], v[210:213], v[62:65]
	v_mfma_f32_16x16x32_bf16 v[86:89], v[142:145], v[214:217], v[86:89]
	v_mfma_f32_16x16x32_bf16 v[86:89], v[146:149], v[218:221], v[86:89]
	v_mfma_f32_16x16x32_bf16 v[54:57], v[150:153], v[214:217], v[54:57]
	v_mfma_f32_16x16x32_bf16 v[54:57], v[154:157], v[218:221], v[54:57]
	v_mfma_f32_16x16x32_bf16 v[78:81], v[142:145], v[222:225], v[78:81]
	v_mfma_f32_16x16x32_bf16 v[78:81], v[146:149], v[226:229], v[78:81]
	v_mfma_f32_16x16x32_bf16 v[50:53], v[150:153], v[222:225], v[50:53]
	v_mfma_f32_16x16x32_bf16 v[50:53], v[154:157], v[226:229], v[50:53]
	v_mfma_f32_16x16x32_bf16 v[46:49], v[158:161], v[198:201], v[46:49]
	v_mfma_f32_16x16x32_bf16 v[46:49], v[162:165], v[202:205], v[46:49]
	v_mfma_f32_16x16x32_bf16 v[14:17], v[174:177], v[198:201], v[14:17]
	v_mfma_f32_16x16x32_bf16 v[14:17], v[188:191], v[202:205], v[14:17]
	v_mfma_f32_16x16x32_bf16 v[42:45], v[158:161], v[206:209], v[42:45]
	v_mfma_f32_16x16x32_bf16 v[42:45], v[162:165], v[210:213], v[42:45]
	v_mfma_f32_16x16x32_bf16 v[10:13], v[174:177], v[206:209], v[10:13]
	v_mfma_f32_16x16x32_bf16 v[10:13], v[188:191], v[210:213], v[10:13]
	v_mfma_f32_16x16x32_bf16 v[38:41], v[158:161], v[214:217], v[38:41]
	v_mfma_f32_16x16x32_bf16 v[38:41], v[162:165], v[218:221], v[38:41]
	v_mfma_f32_16x16x32_bf16 v[6:9], v[174:177], v[214:217], v[6:9]
	v_mfma_f32_16x16x32_bf16 v[6:9], v[188:191], v[218:221], v[6:9]
	v_mfma_f32_16x16x32_bf16 v[34:37], v[158:161], v[222:225], v[34:37]
	v_mfma_f32_16x16x32_bf16 v[34:37], v[162:165], v[226:229], v[34:37]
	v_mfma_f32_16x16x32_bf16 v[2:5], v[174:177], v[222:225], v[2:5]
	v_mfma_f32_16x16x32_bf16 v[2:5], v[188:191], v[226:229], v[2:5]
	s_barrier
; #define PG8_STAGE(bufoff, gbase, voff) do { _Pragma("unroll") for (int _i = 0; _i < 2; ++_i) \
;         __builtin_amdgcn_global_load_lds((const unsigned*)((const char*)(gbase) + (voff)[_i]), (PG8_LAS unsigned*)(lds + (bufoff) + ldsw + _i * 8192), 16, 0, 0); } while (0)
; #define PG8_LDA(dst, b, h) do { _Pragma("unroll") for (int m = 0; m < 4; ++m) _Pragma("unroll") for (int k = 0; k < 2; ++k) dst[m][k] = *(const PG8_LAS bf16x8*)(lds + PG8_SA(b, h) + aoff + m * 2048 + k * 1024); } while (0)
; #define PG8_LDB(dst, b, h) do { _Pragma("unroll") for (int n = 0; n < 2; ++n) _Pragma("unroll") for (int k = 0; k < 2; ++k) dst[n][k] = *(const PG8_LAS bf16x8*)(lds + PG8_SB(b, h) + boff + n * 2048 + k * 1024); } while (0)
; #define PG8_WAIT_V(n) asm volatile("s_waitcnt vmcnt(" #n ")" ::: "memory")
; #define PG8_WAIT_L(n) asm volatile("s_waitcnt lgkmcnt(" #n ")" ::: "memory")
; #define PG8_BAR __builtin_amdgcn_s_barrier()
; #define PG8_SCHED __builtin_amdgcn_sched_barrier(0)
;     ...
;             PG8_LDB(B0, 1, 0); PG8_LDB(B1, 1, 1); PG8_SCHED; PG8_LDA(At, 1, 0); PG8_STAGE(PG8_SA(0, 1), a2 + hstep, voffA);
;             PG8_WAIT_V(8); PG8_WAIT_L(0); PG8_BAR; PG8_MMA(0, 0, At, B0); PG8_MMA(0, 1, At, B1); PG8_BAR; PG8_SCHED;
;             PG8_LDA(At, 1, 1); PG8_STAGE(PG8_SB(1, 0), b3, voffB); PG8_STAGE(PG8_SB(1, 1), b3 + hstep, voffB); PG8_STAGE(PG8_SA(1, 0), a3, voffA);
;             PG8_WAIT_V(8); PG8_WAIT_L(0); PG8_BAR; PG8_MMA(1, 0, At, B0); PG8_MMA(1, 1, At, B1); PG8_BAR; PG8_SCHED;
	s_setprio 0
	s_add_i32 s40, 0, 0x18000
	s_add_i32 s41, 0, 0x1c000
	ds_read_b128 v[142:145], v168 offset:32768
	ds_read_b128 v[146:149], v168 offset:33792
	ds_read_b128 v[150:153], v168 offset:34816
	ds_read_b128 v[154:157], v168 offset:35840
	ds_read_b128 v[158:161], v168 offset:49152
	ds_read_b128 v[162:165], v168 offset:50176
	ds_read_b128 v[174:177], v168 offset:51200
	ds_read_b128 v[188:191], v168 offset:52224
	s_add_u32 s0, s82, 0x80000
	s_addc_u32 s1, s83, 0
	s_mov_b32 m0, s89
	ds_read_b128 v[198:201], v196 offset:32768
	ds_read_b128 v[202:205], v196 offset:33792
	ds_read_b128 v[206:209], v196 offset:34816
	ds_read_b128 v[210:213], v196 offset:35840
	ds_read_b128 v[214:217], v196 offset:36864
	ds_read_b128 v[218:221], v196 offset:37888
	ds_read_b128 v[222:225], v196 offset:38912
	ds_read_b128 v[226:229], v196 offset:39936
	global_load_lds_dwordx4 v130, s[0:1]
	s_mov_b32 m0, s90
	s_nop 0
	global_load_lds_dwordx4 v132, s[0:1]
	s_waitcnt vmcnt(8)
	s_waitcnt lgkmcnt(0)
	s_setprio 1
	s_barrier
	v_mfma_f32_16x16x32_bf16 v[126:129], v[142:145], v[198:201], v[126:129]
	v_mfma_f32_16x16x32_bf16 v[126:129], v[146:149], v[202:205], v[126:129]
	v_mfma_f32_16x16x32_bf16 v[110:113], v[150:153], v[198:201], v[110:113]
	v_mfma_f32_16x16x32_bf16 v[110:113], v[154:157], v[202:205], v[110:113]
	v_mfma_f32_16x16x32_bf16 v[122:125], v[142:145], v[206:209], v[122:125]
	v_mfma_f32_16x16x32_bf16 v[122:125], v[146:149], v[210:213], v[122:125]
	v_mfma_f32_16x16x32_bf16 v[106:109], v[150:153], v[206:209], v[106:109]
	v_mfma_f32_16x16x32_bf16 v[106:109], v[154:157], v[210:213], v[106:109]
	v_mfma_f32_16x16x32_bf16 v[118:121], v[142:145], v[214:217], v[118:121]
	v_mfma_f32_16x16x32_bf16 v[118:121], v[146:149], v[218:221], v[118:121]
	v_mfma_f32_16x16x32_bf16 v[102:105], v[150:153], v[214:217], v[102:105]
	v_mfma_f32_16x16x32_bf16 v[102:105], v[154:157], v[218:221], v[102:105]
	v_mfma_f32_16x16x32_bf16 v[114:117], v[142:145], v[222:225], v[114:117]
	v_mfma_f32_16x16x32_bf16 v[114:117], v[146:149], v[226:229], v[114:117]
	v_mfma_f32_16x16x32_bf16 v[98:101], v[150:153], v[222:225], v[98:101]
	v_mfma_f32_16x16x32_bf16 v[98:101], v[154:157], v[226:229], v[98:101]
	v_mfma_f32_16x16x32_bf16 v[82:85], v[158:161], v[198:201], v[82:85]
	v_mfma_f32_16x16x32_bf16 v[82:85], v[162:165], v[202:205], v[82:85]
	v_mfma_f32_16x16x32_bf16 v[30:33], v[174:177], v[198:201], v[30:33]
	v_mfma_f32_16x16x32_bf16 v[30:33], v[188:191], v[202:205], v[30:33]
	v_mfma_f32_16x16x32_bf16 v[70:73], v[158:161], v[206:209], v[70:73]
	v_mfma_f32_16x16x32_bf16 v[70:73], v[162:165], v[210:213], v[70:73]
	v_mfma_f32_16x16x32_bf16 v[26:29], v[174:177], v[206:209], v[26:29]
	v_mfma_f32_16x16x32_bf16 v[26:29], v[188:191], v[210:213], v[26:29]
	v_mfma_f32_16x16x32_bf16 v[66:69], v[158:161], v[214:217], v[66:69]
	v_mfma_f32_16x16x32_bf16 v[66:69], v[162:165], v[218:221], v[66:69]
	v_mfma_f32_16x16x32_bf16 v[22:25], v[174:177], v[214:217], v[22:25]
	v_mfma_f32_16x16x32_bf16 v[22:25], v[188:191], v[218:221], v[22:25]
	v_mfma_f32_16x16x32_bf16 v[58:61], v[158:161], v[222:225], v[58:61]
	v_mfma_f32_16x16x32_bf16 v[58:61], v[162:165], v[226:229], v[58:61]
	v_mfma_f32_16x16x32_bf16 v[18:21], v[174:177], v[222:225], v[18:21]
	v_mfma_f32_16x16x32_bf16 v[18:21], v[188:191], v[226:229], v[18:21]
	s_barrier
	s_setprio 0
	s_add_i32 s0, s40, s87
	s_mov_b32 m0, s0
	ds_read_b128 v[198:201], v196 offset:49152
	ds_read_b128 v[202:205], v196 offset:50176
	ds_read_b128 v[206:209], v196 offset:51200
	ds_read_b128 v[210:213], v196 offset:52224
	ds_read_b128 v[214:217], v196 offset:53248
	ds_read_b128 v[218:221], v196 offset:54272
	ds_read_b128 v[222:225], v196 offset:55296
	ds_read_b128 v[226:229], v196 offset:56320
	s_add_u32 s100, s80, 0x80
	s_addc_u32 s101, s81, 0
	global_load_lds_dwordx4 v182, s[100:101]
	s_add_i32 m0, s0, 0x2000
	s_add_u32 s0, s80, 0x80080
	s_addc_u32 s1, s81, 0
	s_add_i32 s40, s41, s87
	global_load_lds_dwordx4 v134, s[100:101]
	s_mov_b32 m0, s40
	s_nop 0
	global_load_lds_dwordx4 v182, s[0:1]
	s_add_i32 m0, s40, 0x2000
	s_nop 0
	global_load_lds_dwordx4 v134, s[0:1]
	s_mov_b32 m0, s94
	s_nop 0
	s_add_u32 s100, s82, 0x80
	s_addc_u32 s101, s83, 0
	global_load_lds_dwordx4 v130, s[100:101]
	s_mov_b32 m0, s95
	s_nop 0
	global_load_lds_dwordx4 v132, s[100:101]
	s_waitcnt vmcnt(8)
	s_waitcnt lgkmcnt(0)
	s_setprio 1
	s_barrier
	v_mfma_f32_16x16x32_bf16 v[94:97], v[142:145], v[198:201], v[94:97]
	v_mfma_f32_16x16x32_bf16 v[94:97], v[146:149], v[202:205], v[94:97]
	v_mfma_f32_16x16x32_bf16 v[74:77], v[150:153], v[198:201], v[74:77]
	v_mfma_f32_16x16x32_bf16 v[74:77], v[154:157], v[202:205], v[74:77]
	v_mfma_f32_16x16x32_bf16 v[90:93], v[142:145], v[206:209], v[90:93]
	v_mfma_f32_16x16x32_bf16 v[90:93], v[146:149], v[210:213], v[90:93]
	v_mfma_f32_16x16x32_bf16 v[62:65], v[150:153], v[206:209], v[62:65]
	v_mfma_f32_16x16x32_bf16 v[62:65], v[154:157], v[210:213], v[62:65]
	v_mfma_f32_16x16x32_bf16 v[86:89], v[142:145], v[214:217], v[86:89]
	v_mfma_f32_16x16x32_bf16 v[86:89], v[146:149], v[218:221], v[86:89]
	v_mfma_f32_16x16x32_bf16 v[54:57], v[150:153], v[214:217], v[54:57]
	v_mfma_f32_16x16x32_bf16 v[54:57], v[154:157], v[218:221], v[54:57]
	v_mfma_f32_16x16x32_bf16 v[78:81], v[142:145], v[222:225], v[78:81]
	v_mfma_f32_16x16x32_bf16 v[78:81], v[146:149], v[226:229], v[78:81]
	v_mfma_f32_16x16x32_bf16 v[50:53], v[150:153], v[222:225], v[50:53]
	v_mfma_f32_16x16x32_bf16 v[50:53], v[154:157], v[226:229], v[50:53]
	v_mfma_f32_16x16x32_bf16 v[46:49], v[158:161], v[198:201], v[46:49]
	v_mfma_f32_16x16x32_bf16 v[46:49], v[162:165], v[202:205], v[46:49]
	v_mfma_f32_16x16x32_bf16 v[14:17], v[174:177], v[198:201], v[14:17]
	v_mfma_f32_16x16x32_bf16 v[14:17], v[188:191], v[202:205], v[14:17]
	v_mfma_f32_16x16x32_bf16 v[42:45], v[158:161], v[206:209], v[42:45]
	v_mfma_f32_16x16x32_bf16 v[42:45], v[162:165], v[210:213], v[42:45]
	v_mfma_f32_16x16x32_bf16 v[10:13], v[174:177], v[206:209], v[10:13]
	v_mfma_f32_16x16x32_bf16 v[10:13], v[188:191], v[210:213], v[10:13]
	v_mfma_f32_16x16x32_bf16 v[38:41], v[158:161], v[214:217], v[38:41]
	v_mfma_f32_16x16x32_bf16 v[38:41], v[162:165], v[218:221], v[38:41]
	v_mfma_f32_16x16x32_bf16 v[6:9], v[174:177], v[214:217], v[6:9]
	v_mfma_f32_16x16x32_bf16 v[6:9], v[188:191], v[218:221], v[6:9]
	v_mfma_f32_16x16x32_bf16 v[34:37], v[158:161], v[222:225], v[34:37]
	v_mfma_f32_16x16x32_bf16 v[34:37], v[162:165], v[226:229], v[34:37]
	v_mfma_f32_16x16x32_bf16 v[2:5], v[174:177], v[222:225], v[2:5]
	v_mfma_f32_16x16x32_bf16 v[2:5], v[188:191], v[226:229], v[2:5]
	s_barrier
	s_setprio 0
	s_add_i32 s37, s37, 2
	s_add_u32 s78, s78, 0x100
	s_addc_u32 s79, s79, 0
	s_add_u32 s33, s33, 0x100
	s_addc_u32 s35, s35, 0
	s_cmp_gt_u32 s37, 29
	s_cbranch_scc0 .LBB0_234
	s_and_b64 vcc, exec, s[64:65]
	s_cbranch_vccz .LBB0_237
	s_barrier

; #define PG8_STAGE(bufoff, gbase, voff) do { _Pragma("unroll") for (int _i = 0; _i < 2; ++_i) \
;         __builtin_amdgcn_global_load_lds((const unsigned*)((const char*)(gbase) + (voff)[_i]), (PG8_LAS unsigned*)(lds + (bufoff) + ldsw + _i * 8192), 16, 0, 0); } while (0)
; #define PG8_LDA(dst, b, h) do { _Pragma("unroll") for (int m = 0; m < 4; ++m) _Pragma("unroll") for (int k = 0; k < 2; ++k) dst[m][k] = *(const PG8_LAS bf16x8*)(lds + PG8_SA(b, h) + aoff + m * 2048 + k * 1024); } while (0)
; #define PG8_LDB(dst, b, h) do { _Pragma("unroll") for (int n = 0; n < 2; ++n) _Pragma("unroll") for (int k = 0; k < 2; ++k) dst[n][k] = *(const PG8_LAS bf16x8*)(lds + PG8_SB(b, h) + boff + n * 2048 + k * 1024); } while (0)
; #define PG8_WAIT_L(n) asm volatile("s_waitcnt lgkmcnt(" #n ")" ::: "memory")
; #define PG8_WAIT_V_SEL(sel) asm volatile("s_cmp_eq_u32 %0, 0\n\ts_cbranch_scc1 .Lw8_%=\n\ts_waitcnt vmcnt(22)\n\ts_branch .Lwd_%=\n.Lw8_%=:\n\ts_waitcnt vmcnt(8)\n.Lwd_%=:" :: "s"(sel) : "memory", "scc")
; #define PG8_BAR __builtin_amdgcn_s_barrier()
; #define PG8_SCHED __builtin_amdgcn_sched_barrier(0)
;     ...
;             PG8_LDB(B0, 0, 0); PG8_LDB(B1, 0, 1); PG8_SCHED; PG8_LDA(At, 0, 0); PG8_STAGE(PG8_SA(1, 1), a1 + hstep, voffA);
;             PG8_WAIT_V_SEL(relax);
;             PG8_WAIT_L(0); PG8_BAR; PG8_MMA(0, 0, At, B0); PG8_MMA(0, 1, At, B1); PG8_BAR; PG8_SCHED;
;             PG8_LDA(At, 0, 1); PG8_STAGE(PG8_SB(0, 0), b2, voffB); PG8_STAGE(PG8_SB(0, 1), b2 + hstep, voffB); PG8_STAGE(PG8_SA(0, 0), a2, voffA);
;             PG8_WAIT_V_SEL(relax);
;             PG8_WAIT_L(0); PG8_BAR; PG8_MMA(1, 0, At, B0); PG8_MMA(1, 1, At, B1); PG8_BAR; PG8_SCHED;
.LBB0_541:
	s_add_u32 s0, s82, 0xfff80080
	s_addc_u32 s1, s83, -1
	s_add_i32 s79, 0, 0x10000
	s_cmp_eq_u32 s73, 28
	s_cselect_b32 s87, s40, s1
	s_cselect_b32 s86, s41, s0
	s_cselect_b32 s85, s57, s71
	s_cselect_b32 s84, s58, s59
	s_add_i32 s81, 0, 0x14000
	ds_read_b128 v[90:93], v210
	ds_read_b128 v[94:97], v210 offset:1024
	ds_read_b128 v[98:101], v210 offset:2048
	ds_read_b128 v[102:105], v210 offset:3072
	ds_read_b128 v[146:149], v210 offset:16384
	ds_read_b128 v[150:153], v210 offset:17408
	ds_read_b128 v[154:157], v210 offset:18432
	ds_read_b128 v[158:161], v210 offset:19456
	s_add_i32 m0, s44, 0xc000
	ds_read_b128 v[162:165], v230
	ds_read_b128 v[166:169], v230 offset:1024
	ds_read_b128 v[184:187], v230 offset:2048
	ds_read_b128 v[190:193], v230 offset:3072
	ds_read_b128 v[194:197], v230 offset:4096
	ds_read_b128 v[198:201], v230 offset:5120
	ds_read_b128 v[202:205], v230 offset:6144
	ds_read_b128 v[206:209], v230 offset:7168
	global_load_lds_dwordx4 v180, s[82:83]
	s_add_i32 m0, s44, 0xe000
	s_nop 0
	global_load_lds_dwordx4 v188, s[82:83]
	s_waitcnt vmcnt(8)
	s_waitcnt lgkmcnt(0)
	s_setprio 1
	s_barrier
	v_mfma_f32_16x16x32_bf16 v[142:145], v[90:93], v[162:165], v[142:145]
	v_mfma_f32_16x16x32_bf16 v[142:145], v[94:97], v[166:169], v[142:145]
	v_mfma_f32_16x16x32_bf16 v[138:141], v[98:101], v[162:165], v[138:141]
	v_mfma_f32_16x16x32_bf16 v[138:141], v[102:105], v[166:169], v[138:141]
	v_mfma_f32_16x16x32_bf16 v[126:129], v[90:93], v[184:187], v[126:129]
	v_mfma_f32_16x16x32_bf16 v[126:129], v[94:97], v[190:193], v[126:129]
	v_mfma_f32_16x16x32_bf16 v[122:125], v[98:101], v[184:187], v[122:125]
	v_mfma_f32_16x16x32_bf16 v[122:125], v[102:105], v[190:193], v[122:125]
	v_mfma_f32_16x16x32_bf16 v[110:113], v[90:93], v[194:197], v[110:113]
	v_mfma_f32_16x16x32_bf16 v[110:113], v[94:97], v[198:201], v[110:113]
	v_mfma_f32_16x16x32_bf16 v[106:109], v[98:101], v[194:197], v[106:109]
	v_mfma_f32_16x16x32_bf16 v[106:109], v[102:105], v[198:201], v[106:109]
	v_mfma_f32_16x16x32_bf16 v[78:81], v[90:93], v[202:205], v[78:81]
	v_mfma_f32_16x16x32_bf16 v[78:81], v[94:97], v[206:209], v[78:81]
	v_mfma_f32_16x16x32_bf16 v[74:77], v[98:101], v[202:205], v[74:77]
	v_mfma_f32_16x16x32_bf16 v[74:77], v[102:105], v[206:209], v[74:77]
	v_mfma_f32_16x16x32_bf16 v[134:137], v[146:149], v[162:165], v[134:137]
	v_mfma_f32_16x16x32_bf16 v[134:137], v[150:153], v[166:169], v[134:137]
	v_mfma_f32_16x16x32_bf16 v[130:133], v[154:157], v[162:165], v[130:133]
	v_mfma_f32_16x16x32_bf16 v[130:133], v[158:161], v[166:169], v[130:133]
	v_mfma_f32_16x16x32_bf16 v[118:121], v[146:149], v[184:187], v[118:121]
	v_mfma_f32_16x16x32_bf16 v[118:121], v[150:153], v[190:193], v[118:121]
	v_mfma_f32_16x16x32_bf16 v[114:117], v[154:157], v[184:187], v[114:117]
	v_mfma_f32_16x16x32_bf16 v[114:117], v[158:161], v[190:193], v[114:117]
	v_mfma_f32_16x16x32_bf16 v[86:89], v[146:149], v[194:197], v[86:89]
	v_mfma_f32_16x16x32_bf16 v[86:89], v[150:153], v[198:201], v[86:89]
	v_mfma_f32_16x16x32_bf16 v[82:85], v[154:157], v[194:197], v[82:85]
	v_mfma_f32_16x16x32_bf16 v[82:85], v[158:161], v[198:201], v[82:85]
	v_mfma_f32_16x16x32_bf16 v[70:73], v[146:149], v[202:205], v[70:73]
	v_mfma_f32_16x16x32_bf16 v[70:73], v[150:153], v[206:209], v[70:73]
	v_mfma_f32_16x16x32_bf16 v[66:69], v[154:157], v[202:205], v[66:69]
	v_mfma_f32_16x16x32_bf16 v[66:69], v[158:161], v[206:209], v[66:69]
	s_barrier
	s_setprio 0
	s_add_i32 s0, s79, s30
	s_mov_b32 m0, s0
	ds_read_b128 v[162:165], v230 offset:16384
	ds_read_b128 v[166:169], v230 offset:17408
	ds_read_b128 v[184:187], v230 offset:18432
	ds_read_b128 v[190:193], v230 offset:19456
	ds_read_b128 v[194:197], v230 offset:20480
	ds_read_b128 v[198:201], v230 offset:21504
	ds_read_b128 v[202:205], v230 offset:22528
	ds_read_b128 v[206:209], v230 offset:23552
	global_load_lds_dwordx4 v182, s[84:85]
	s_add_i32 m0, s0, 0x2000
	s_add_u32 s0, s84, 0x80000
	s_addc_u32 s1, s85, 0
	s_add_i32 s79, s81, s30
	global_load_lds_dwordx4 v178, s[84:85]
	s_mov_b32 m0, s79
	s_nop 0
	global_load_lds_dwordx4 v182, s[0:1]
	s_add_i32 m0, s79, 0x2000
	s_nop 0
	global_load_lds_dwordx4 v178, s[0:1]
	s_mov_b32 m0, s44
	s_nop 0
	global_load_lds_dwordx4 v174, s[86:87]
	s_mov_b32 m0, s45
	s_nop 0
	global_load_lds_dwordx4 v176, s[86:87]
	s_waitcnt vmcnt(8)
	s_waitcnt lgkmcnt(0)
	s_setprio 1
	s_barrier
	v_mfma_f32_16x16x32_bf16 v[62:65], v[90:93], v[162:165], v[62:65]
	v_mfma_f32_16x16x32_bf16 v[62:65], v[94:97], v[166:169], v[62:65]
	v_mfma_f32_16x16x32_bf16 v[58:61], v[98:101], v[162:165], v[58:61]
	v_mfma_f32_16x16x32_bf16 v[58:61], v[102:105], v[166:169], v[58:61]
	v_mfma_f32_16x16x32_bf16 v[46:49], v[90:93], v[184:187], v[46:49]
	v_mfma_f32_16x16x32_bf16 v[46:49], v[94:97], v[190:193], v[46:49]
	v_mfma_f32_16x16x32_bf16 v[42:45], v[98:101], v[184:187], v[42:45]
	v_mfma_f32_16x16x32_bf16 v[42:45], v[102:105], v[190:193], v[42:45]
	v_mfma_f32_16x16x32_bf16 v[30:33], v[90:93], v[194:197], v[30:33]
	v_mfma_f32_16x16x32_bf16 v[30:33], v[94:97], v[198:201], v[30:33]
	v_mfma_f32_16x16x32_bf16 v[26:29], v[98:101], v[194:197], v[26:29]
	v_mfma_f32_16x16x32_bf16 v[26:29], v[102:105], v[198:201], v[26:29]
	v_mfma_f32_16x16x32_bf16 v[14:17], v[90:93], v[202:205], v[14:17]
	v_mfma_f32_16x16x32_bf16 v[14:17], v[94:97], v[206:209], v[14:17]
	v_mfma_f32_16x16x32_bf16 v[10:13], v[98:101], v[202:205], v[10:13]
	v_mfma_f32_16x16x32_bf16 v[10:13], v[102:105], v[206:209], v[10:13]
	v_mfma_f32_16x16x32_bf16 v[54:57], v[146:149], v[162:165], v[54:57]
	v_mfma_f32_16x16x32_bf16 v[54:57], v[150:153], v[166:169], v[54:57]
	v_mfma_f32_16x16x32_bf16 v[50:53], v[154:157], v[162:165], v[50:53]
	v_mfma_f32_16x16x32_bf16 v[50:53], v[158:161], v[166:169], v[50:53]
	v_mfma_f32_16x16x32_bf16 v[38:41], v[146:149], v[184:187], v[38:41]
	v_mfma_f32_16x16x32_bf16 v[38:41], v[150:153], v[190:193], v[38:41]
	v_mfma_f32_16x16x32_bf16 v[34:37], v[154:157], v[184:187], v[34:37]
	v_mfma_f32_16x16x32_bf16 v[34:37], v[158:161], v[190:193], v[34:37]
	v_mfma_f32_16x16x32_bf16 v[22:25], v[146:149], v[194:197], v[22:25]
	v_mfma_f32_16x16x32_bf16 v[22:25], v[150:153], v[198:201], v[22:25]
	v_mfma_f32_16x16x32_bf16 v[18:21], v[154:157], v[194:197], v[18:21]
	v_mfma_f32_16x16x32_bf16 v[18:21], v[158:161], v[198:201], v[18:21]
	v_mfma_f32_16x16x32_bf16 v[6:9], v[146:149], v[202:205], v[6:9]
	v_mfma_f32_16x16x32_bf16 v[6:9], v[150:153], v[206:209], v[6:9]
	v_mfma_f32_16x16x32_bf16 v[2:5], v[154:157], v[202:205], v[2:5]
	v_mfma_f32_16x16x32_bf16 v[2:5], v[158:161], v[206:209], v[2:5]
	s_barrier
; #define PG8_STAGE(bufoff, gbase, voff) do { _Pragma("unroll") for (int _i = 0; _i < 2; ++_i) \
;         __builtin_amdgcn_global_load_lds((const unsigned*)((const char*)(gbase) + (voff)[_i]), (PG8_LAS unsigned*)(lds + (bufoff) + ldsw + _i * 8192), 16, 0, 0); } while (0)
; #define PG8_LDA(dst, b, h) do { _Pragma("unroll") for (int m = 0; m < 4; ++m) _Pragma("unroll") for (int k = 0; k < 2; ++k) dst[m][k] = *(const PG8_LAS bf16x8*)(lds + PG8_SA(b, h) + aoff + m * 2048 + k * 1024); } while (0)
; #define PG8_LDB(dst, b, h) do { _Pragma("unroll") for (int n = 0; n < 2; ++n) _Pragma("unroll") for (int k = 0; k < 2; ++k) dst[n][k] = *(const PG8_LAS bf16x8*)(lds + PG8_SB(b, h) + boff + n * 2048 + k * 1024); } while (0)
; #define PG8_WAIT_V(n) asm volatile("s_waitcnt vmcnt(" #n ")" ::: "memory")
; #define PG8_WAIT_L(n) asm volatile("s_waitcnt lgkmcnt(" #n ")" ::: "memory")
; #define PG8_BAR __builtin_amdgcn_s_barrier()
; #define PG8_SCHED __builtin_amdgcn_sched_barrier(0)
;     ...
;             PG8_LDB(B0, 1, 0); PG8_LDB(B1, 1, 1); PG8_SCHED; PG8_LDA(At, 1, 0); PG8_STAGE(PG8_SA(0, 1), a2 + hstep, voffA);
;             PG8_WAIT_V(8); PG8_WAIT_L(0); PG8_BAR; PG8_MMA(0, 0, At, B0); PG8_MMA(0, 1, At, B1); PG8_BAR; PG8_SCHED;
;             PG8_LDA(At, 1, 1); PG8_STAGE(PG8_SB(1, 0), b3, voffB); PG8_STAGE(PG8_SB(1, 1), b3 + hstep, voffB); PG8_STAGE(PG8_SA(1, 0), a3, voffA);
;             PG8_WAIT_V(8); PG8_WAIT_L(0); PG8_BAR; PG8_MMA(1, 0, At, B0); PG8_MMA(1, 1, At, B1); PG8_BAR; PG8_SCHED;
	s_setprio 0
	s_add_i32 s79, 0, 0x18000
	s_add_i32 s81, 0, 0x1c000
	ds_read_b128 v[90:93], v210 offset:32768
	ds_read_b128 v[94:97], v210 offset:33792
	ds_read_b128 v[98:101], v210 offset:34816
	ds_read_b128 v[102:105], v210 offset:35840
	ds_read_b128 v[146:149], v210 offset:49152
	ds_read_b128 v[150:153], v210 offset:50176
	ds_read_b128 v[154:157], v210 offset:51200
	ds_read_b128 v[158:161], v210 offset:52224
	s_add_u32 s0, s86, 0x80000
	s_addc_u32 s1, s87, 0
	s_mov_b32 m0, s46
	ds_read_b128 v[162:165], v230 offset:32768
	ds_read_b128 v[166:169], v230 offset:33792
	ds_read_b128 v[184:187], v230 offset:34816
	ds_read_b128 v[190:193], v230 offset:35840
	ds_read_b128 v[194:197], v230 offset:36864
	ds_read_b128 v[198:201], v230 offset:37888
	ds_read_b128 v[202:205], v230 offset:38912
	ds_read_b128 v[206:209], v230 offset:39936
	global_load_lds_dwordx4 v174, s[0:1]
	s_mov_b32 m0, s47
	s_nop 0
	global_load_lds_dwordx4 v176, s[0:1]
	s_waitcnt vmcnt(8)
	s_waitcnt lgkmcnt(0)
	s_setprio 1
	s_barrier
	v_mfma_f32_16x16x32_bf16 v[142:145], v[90:93], v[162:165], v[142:145]
	v_mfma_f32_16x16x32_bf16 v[142:145], v[94:97], v[166:169], v[142:145]
	v_mfma_f32_16x16x32_bf16 v[138:141], v[98:101], v[162:165], v[138:141]
	v_mfma_f32_16x16x32_bf16 v[138:141], v[102:105], v[166:169], v[138:141]
	v_mfma_f32_16x16x32_bf16 v[126:129], v[90:93], v[184:187], v[126:129]
	v_mfma_f32_16x16x32_bf16 v[126:129], v[94:97], v[190:193], v[126:129]
	v_mfma_f32_16x16x32_bf16 v[122:125], v[98:101], v[184:187], v[122:125]
	v_mfma_f32_16x16x32_bf16 v[122:125], v[102:105], v[190:193], v[122:125]
	v_mfma_f32_16x16x32_bf16 v[110:113], v[90:93], v[194:197], v[110:113]
	v_mfma_f32_16x16x32_bf16 v[110:113], v[94:97], v[198:201], v[110:113]
	v_mfma_f32_16x16x32_bf16 v[106:109], v[98:101], v[194:197], v[106:109]
	v_mfma_f32_16x16x32_bf16 v[106:109], v[102:105], v[198:201], v[106:109]
	v_mfma_f32_16x16x32_bf16 v[78:81], v[90:93], v[202:205], v[78:81]
	v_mfma_f32_16x16x32_bf16 v[78:81], v[94:97], v[206:209], v[78:81]
	v_mfma_f32_16x16x32_bf16 v[74:77], v[98:101], v[202:205], v[74:77]
	v_mfma_f32_16x16x32_bf16 v[74:77], v[102:105], v[206:209], v[74:77]
	v_mfma_f32_16x16x32_bf16 v[134:137], v[146:149], v[162:165], v[134:137]
	v_mfma_f32_16x16x32_bf16 v[134:137], v[150:153], v[166:169], v[134:137]
	v_mfma_f32_16x16x32_bf16 v[130:133], v[154:157], v[162:165], v[130:133]
	v_mfma_f32_16x16x32_bf16 v[130:133], v[158:161], v[166:169], v[130:133]
	v_mfma_f32_16x16x32_bf16 v[118:121], v[146:149], v[184:187], v[118:121]
	v_mfma_f32_16x16x32_bf16 v[118:121], v[150:153], v[190:193], v[118:121]
	v_mfma_f32_16x16x32_bf16 v[114:117], v[154:157], v[184:187], v[114:117]
	v_mfma_f32_16x16x32_bf16 v[114:117], v[158:161], v[190:193], v[114:117]
	v_mfma_f32_16x16x32_bf16 v[86:89], v[146:149], v[194:197], v[86:89]
	v_mfma_f32_16x16x32_bf16 v[86:89], v[150:153], v[198:201], v[86:89]
	v_mfma_f32_16x16x32_bf16 v[82:85], v[154:157], v[194:197], v[82:85]
	v_mfma_f32_16x16x32_bf16 v[82:85], v[158:161], v[198:201], v[82:85]
	v_mfma_f32_16x16x32_bf16 v[70:73], v[146:149], v[202:205], v[70:73]
	v_mfma_f32_16x16x32_bf16 v[70:73], v[150:153], v[206:209], v[70:73]
	v_mfma_f32_16x16x32_bf16 v[66:69], v[154:157], v[202:205], v[66:69]
	v_mfma_f32_16x16x32_bf16 v[66:69], v[158:161], v[206:209], v[66:69]
	s_barrier
	s_setprio 0
	s_add_i32 s0, s79, s30
	s_mov_b32 m0, s0
	ds_read_b128 v[162:165], v230 offset:49152
	ds_read_b128 v[166:169], v230 offset:50176
	ds_read_b128 v[184:187], v230 offset:51200
	ds_read_b128 v[190:193], v230 offset:52224
	ds_read_b128 v[194:197], v230 offset:53248
	ds_read_b128 v[198:201], v230 offset:54272
	ds_read_b128 v[202:205], v230 offset:55296
	ds_read_b128 v[206:209], v230 offset:56320
	s_add_u32 s100, s84, 0x80
	s_addc_u32 s101, s85, 0
	global_load_lds_dwordx4 v182, s[100:101]
	s_add_i32 m0, s0, 0x2000
	s_add_u32 s0, s84, 0x80080
	s_addc_u32 s1, s85, 0
	s_add_i32 s79, s81, s30
	global_load_lds_dwordx4 v178, s[100:101]
	s_mov_b32 m0, s79
	s_nop 0
	global_load_lds_dwordx4 v182, s[0:1]
	s_add_i32 m0, s79, 0x2000
	s_nop 0
	global_load_lds_dwordx4 v178, s[0:1]
	s_mov_b32 m0, s49
	s_nop 0
	s_add_u32 s100, s86, 0x80
	s_addc_u32 s101, s87, 0
	global_load_lds_dwordx4 v174, s[100:101]
	s_mov_b32 m0, s50
	s_nop 0
	global_load_lds_dwordx4 v176, s[100:101]
	s_waitcnt vmcnt(8)
	s_waitcnt lgkmcnt(0)
	s_setprio 1
	s_barrier
	v_mfma_f32_16x16x32_bf16 v[62:65], v[90:93], v[162:165], v[62:65]
	v_mfma_f32_16x16x32_bf16 v[62:65], v[94:97], v[166:169], v[62:65]
	v_mfma_f32_16x16x32_bf16 v[58:61], v[98:101], v[162:165], v[58:61]
	v_mfma_f32_16x16x32_bf16 v[58:61], v[102:105], v[166:169], v[58:61]
	v_mfma_f32_16x16x32_bf16 v[46:49], v[90:93], v[184:187], v[46:49]
	v_mfma_f32_16x16x32_bf16 v[46:49], v[94:97], v[190:193], v[46:49]
	v_mfma_f32_16x16x32_bf16 v[42:45], v[98:101], v[184:187], v[42:45]
	v_mfma_f32_16x16x32_bf16 v[42:45], v[102:105], v[190:193], v[42:45]
	v_mfma_f32_16x16x32_bf16 v[30:33], v[90:93], v[194:197], v[30:33]
	v_mfma_f32_16x16x32_bf16 v[30:33], v[94:97], v[198:201], v[30:33]
	v_mfma_f32_16x16x32_bf16 v[26:29], v[98:101], v[194:197], v[26:29]
	v_mfma_f32_16x16x32_bf16 v[26:29], v[102:105], v[198:201], v[26:29]
	v_mfma_f32_16x16x32_bf16 v[14:17], v[90:93], v[202:205], v[14:17]
	v_mfma_f32_16x16x32_bf16 v[14:17], v[94:97], v[206:209], v[14:17]
	v_mfma_f32_16x16x32_bf16 v[10:13], v[98:101], v[202:205], v[10:13]
	v_mfma_f32_16x16x32_bf16 v[10:13], v[102:105], v[206:209], v[10:13]
	v_mfma_f32_16x16x32_bf16 v[54:57], v[146:149], v[162:165], v[54:57]
	v_mfma_f32_16x16x32_bf16 v[54:57], v[150:153], v[166:169], v[54:57]
	v_mfma_f32_16x16x32_bf16 v[50:53], v[154:157], v[162:165], v[50:53]
	v_mfma_f32_16x16x32_bf16 v[50:53], v[158:161], v[166:169], v[50:53]
	v_mfma_f32_16x16x32_bf16 v[38:41], v[146:149], v[184:187], v[38:41]
	v_mfma_f32_16x16x32_bf16 v[38:41], v[150:153], v[190:193], v[38:41]
	v_mfma_f32_16x16x32_bf16 v[34:37], v[154:157], v[184:187], v[34:37]
	v_mfma_f32_16x16x32_bf16 v[34:37], v[158:161], v[190:193], v[34:37]
	v_mfma_f32_16x16x32_bf16 v[22:25], v[146:149], v[194:197], v[22:25]
	v_mfma_f32_16x16x32_bf16 v[22:25], v[150:153], v[198:201], v[22:25]
	v_mfma_f32_16x16x32_bf16 v[18:21], v[154:157], v[194:197], v[18:21]
	v_mfma_f32_16x16x32_bf16 v[18:21], v[158:161], v[198:201], v[18:21]
	v_mfma_f32_16x16x32_bf16 v[6:9], v[146:149], v[202:205], v[6:9]
	v_mfma_f32_16x16x32_bf16 v[6:9], v[150:153], v[206:209], v[6:9]
	v_mfma_f32_16x16x32_bf16 v[2:5], v[154:157], v[202:205], v[2:5]
	v_mfma_f32_16x16x32_bf16 v[2:5], v[158:161], v[206:209], v[2:5]
	s_barrier
	s_setprio 0
	s_add_i32 s73, s73, 2
	s_add_u32 s82, s82, 0x100
	s_addc_u32 s83, s83, 0
	s_add_u32 s59, s59, 0x100
	s_addc_u32 s71, s71, 0
	s_cmp_gt_u32 s73, 29
	s_cbranch_scc0 .LBB0_541
	s_and_b64 vcc, exec, s[68:69]
	s_cbranch_vccz .LBB0_544
	s_barrier

; #define PG8_STAGE(bufoff, gbase, voff) do { _Pragma("unroll") for (int _i = 0; _i < 2; ++_i) \
;         __builtin_amdgcn_global_load_lds((const unsigned*)((const char*)(gbase) + (voff)[_i]), (PG8_LAS unsigned*)(lds + (bufoff) + ldsw + _i * 8192), 16, 0, 0); } while (0)
; #define PG8_LDA(dst, b, h) do { _Pragma("unroll") for (int m = 0; m < 4; ++m) _Pragma("unroll") for (int k = 0; k < 2; ++k) dst[m][k] = *(const PG8_LAS bf16x8*)(lds + PG8_SA(b, h) + aoff + m * 2048 + k * 1024); } while (0)
; #define PG8_LDB(dst, b, h) do { _Pragma("unroll") for (int n = 0; n < 2; ++n) _Pragma("unroll") for (int k = 0; k < 2; ++k) dst[n][k] = *(const PG8_LAS bf16x8*)(lds + PG8_SB(b, h) + boff + n * 2048 + k * 1024); } while (0)
; #define PG8_WAIT_L(n) asm volatile("s_waitcnt lgkmcnt(" #n ")" ::: "memory")
; #define PG8_WAIT_V_SEL(sel) asm volatile("s_cmp_eq_u32 %0, 0\n\ts_cbranch_scc1 .Lw8_%=\n\ts_waitcnt vmcnt(22)\n\ts_branch .Lwd_%=\n.Lw8_%=:\n\ts_waitcnt vmcnt(8)\n.Lwd_%=:" :: "s"(sel) : "memory", "scc")
; #define PG8_BAR __builtin_amdgcn_s_barrier()
; #define PG8_SCHED __builtin_amdgcn_sched_barrier(0)
;     ...
;             PG8_LDB(B0, 0, 0); PG8_LDB(B1, 0, 1); PG8_SCHED; PG8_LDA(At, 0, 0); PG8_STAGE(PG8_SA(1, 1), a1 + hstep, voffA);
;             PG8_WAIT_V_SEL(relax);
;             PG8_WAIT_L(0); PG8_BAR; PG8_MMA(0, 0, At, B0); PG8_MMA(0, 1, At, B1); PG8_BAR; PG8_SCHED;
;             PG8_LDA(At, 0, 1); PG8_STAGE(PG8_SB(0, 0), b2, voffB); PG8_STAGE(PG8_SB(0, 1), b2 + hstep, voffB); PG8_STAGE(PG8_SA(0, 0), a2, voffA);
;             PG8_WAIT_V_SEL(relax);
;             PG8_WAIT_L(0); PG8_BAR; PG8_MMA(1, 0, At, B0); PG8_MMA(1, 1, At, B1); PG8_BAR; PG8_SCHED;
.LBB0_596:
	s_add_u32 s0, s74, 0xfff80080
	s_addc_u32 s1, s75, -1
	s_add_i32 s83, 0, 0x10000
	s_cmp_eq_u32 s82, 28
	s_cselect_b32 s79, s40, s1
	s_cselect_b32 s78, s41, s0
	s_cselect_b32 s77, s65, s81
	s_cselect_b32 s76, s73, s80
	s_add_i32 s84, 0, 0x14000
	ds_read_b128 v[150:153], v180
	ds_read_b128 v[154:157], v180 offset:1024
	ds_read_b128 v[158:161], v180 offset:2048
	ds_read_b128 v[162:165], v180 offset:3072
	ds_read_b128 v[166:169], v180 offset:16384
	ds_read_b128 v[172:175], v180 offset:17408
	ds_read_b128 v[176:179], v180 offset:18432
	ds_read_b128 v[188:191], v180 offset:19456
	s_add_i32 m0, s35, 0xc000
	ds_read_b128 v[192:195], v148
	ds_read_b128 v[196:199], v148 offset:1024
	ds_read_b128 v[200:203], v148 offset:2048
	ds_read_b128 v[204:207], v148 offset:3072
	ds_read_b128 v[208:211], v148 offset:4096
	ds_read_b128 v[212:215], v148 offset:5120
	ds_read_b128 v[216:219], v148 offset:6144
	ds_read_b128 v[220:223], v148 offset:7168
	global_load_lds_dwordx4 v140, s[74:75]
	s_add_i32 m0, s35, 0xe000
	s_nop 0
	global_load_lds_dwordx4 v142, s[74:75]
	s_waitcnt vmcnt(8)
	s_waitcnt lgkmcnt(0)
	s_setprio 1
	s_barrier
	v_mfma_f32_16x16x32_bf16 v[126:129], v[150:153], v[192:195], v[126:129]
	v_mfma_f32_16x16x32_bf16 v[126:129], v[154:157], v[196:199], v[126:129]
	v_mfma_f32_16x16x32_bf16 v[110:113], v[158:161], v[192:195], v[110:113]
	v_mfma_f32_16x16x32_bf16 v[110:113], v[162:165], v[196:199], v[110:113]
	v_mfma_f32_16x16x32_bf16 v[122:125], v[150:153], v[200:203], v[122:125]
	v_mfma_f32_16x16x32_bf16 v[122:125], v[154:157], v[204:207], v[122:125]
	v_mfma_f32_16x16x32_bf16 v[106:109], v[158:161], v[200:203], v[106:109]
	v_mfma_f32_16x16x32_bf16 v[106:109], v[162:165], v[204:207], v[106:109]
	v_mfma_f32_16x16x32_bf16 v[118:121], v[150:153], v[208:211], v[118:121]
	v_mfma_f32_16x16x32_bf16 v[118:121], v[154:157], v[212:215], v[118:121]
	v_mfma_f32_16x16x32_bf16 v[102:105], v[158:161], v[208:211], v[102:105]
	v_mfma_f32_16x16x32_bf16 v[102:105], v[162:165], v[212:215], v[102:105]
	v_mfma_f32_16x16x32_bf16 v[114:117], v[150:153], v[216:219], v[114:117]
	v_mfma_f32_16x16x32_bf16 v[114:117], v[154:157], v[220:223], v[114:117]
	v_mfma_f32_16x16x32_bf16 v[98:101], v[158:161], v[216:219], v[98:101]
	v_mfma_f32_16x16x32_bf16 v[98:101], v[162:165], v[220:223], v[98:101]
	v_mfma_f32_16x16x32_bf16 v[70:73], v[166:169], v[192:195], v[70:73]
	v_mfma_f32_16x16x32_bf16 v[70:73], v[172:175], v[196:199], v[70:73]
	v_mfma_f32_16x16x32_bf16 v[50:53], v[176:179], v[192:195], v[50:53]
	v_mfma_f32_16x16x32_bf16 v[50:53], v[188:191], v[196:199], v[50:53]
	v_mfma_f32_16x16x32_bf16 v[66:69], v[166:169], v[200:203], v[66:69]
	v_mfma_f32_16x16x32_bf16 v[66:69], v[172:175], v[204:207], v[66:69]
	v_mfma_f32_16x16x32_bf16 v[42:45], v[176:179], v[200:203], v[42:45]
	v_mfma_f32_16x16x32_bf16 v[42:45], v[188:191], v[204:207], v[42:45]
	v_mfma_f32_16x16x32_bf16 v[58:61], v[166:169], v[208:211], v[58:61]
	v_mfma_f32_16x16x32_bf16 v[58:61], v[172:175], v[212:215], v[58:61]
	v_mfma_f32_16x16x32_bf16 v[38:41], v[176:179], v[208:211], v[38:41]
	v_mfma_f32_16x16x32_bf16 v[38:41], v[188:191], v[212:215], v[38:41]
	v_mfma_f32_16x16x32_bf16 v[46:49], v[166:169], v[216:219], v[46:49]
	v_mfma_f32_16x16x32_bf16 v[46:49], v[172:175], v[220:223], v[46:49]
	v_mfma_f32_16x16x32_bf16 v[34:37], v[176:179], v[216:219], v[34:37]
	v_mfma_f32_16x16x32_bf16 v[34:37], v[188:191], v[220:223], v[34:37]
	s_barrier
	s_setprio 0
	s_add_i32 s0, s83, s20
	s_mov_b32 m0, s0
	ds_read_b128 v[192:195], v148 offset:16384
	ds_read_b128 v[196:199], v148 offset:17408
	ds_read_b128 v[200:203], v148 offset:18432
	ds_read_b128 v[204:207], v148 offset:19456
	ds_read_b128 v[208:211], v148 offset:20480
	ds_read_b128 v[212:215], v148 offset:21504
	ds_read_b128 v[216:219], v148 offset:22528
	ds_read_b128 v[220:223], v148 offset:23552
	global_load_lds_dwordx4 v132, s[76:77]
	s_add_i32 m0, s0, 0x2000
	s_add_u32 s0, s76, 0x80000
	s_addc_u32 s1, s77, 0
	s_add_i32 s83, s84, s20
	global_load_lds_dwordx4 v136, s[76:77]
	s_mov_b32 m0, s83
	s_nop 0
	global_load_lds_dwordx4 v132, s[0:1]
	s_add_i32 m0, s83, 0x2000
	s_nop 0
	global_load_lds_dwordx4 v136, s[0:1]
	s_mov_b32 m0, s35
	s_nop 0
	global_load_lds_dwordx4 v130, s[78:79]
	s_mov_b32 m0, s37
	s_nop 0
	global_load_lds_dwordx4 v134, s[78:79]
	s_waitcnt vmcnt(8)
	s_waitcnt lgkmcnt(0)
	s_setprio 1
	s_barrier
	v_mfma_f32_16x16x32_bf16 v[94:97], v[150:153], v[192:195], v[94:97]
	v_mfma_f32_16x16x32_bf16 v[94:97], v[154:157], v[196:199], v[94:97]
	v_mfma_f32_16x16x32_bf16 v[78:81], v[158:161], v[192:195], v[78:81]
	v_mfma_f32_16x16x32_bf16 v[78:81], v[162:165], v[196:199], v[78:81]
	v_mfma_f32_16x16x32_bf16 v[90:93], v[150:153], v[200:203], v[90:93]
	v_mfma_f32_16x16x32_bf16 v[90:93], v[154:157], v[204:207], v[90:93]
	v_mfma_f32_16x16x32_bf16 v[74:77], v[158:161], v[200:203], v[74:77]
	v_mfma_f32_16x16x32_bf16 v[74:77], v[162:165], v[204:207], v[74:77]
	v_mfma_f32_16x16x32_bf16 v[86:89], v[150:153], v[208:211], v[86:89]
	v_mfma_f32_16x16x32_bf16 v[86:89], v[154:157], v[212:215], v[86:89]
	v_mfma_f32_16x16x32_bf16 v[62:65], v[158:161], v[208:211], v[62:65]
	v_mfma_f32_16x16x32_bf16 v[62:65], v[162:165], v[212:215], v[62:65]
	v_mfma_f32_16x16x32_bf16 v[82:85], v[150:153], v[216:219], v[82:85]
	v_mfma_f32_16x16x32_bf16 v[82:85], v[154:157], v[220:223], v[82:85]
	v_mfma_f32_16x16x32_bf16 v[54:57], v[158:161], v[216:219], v[54:57]
	v_mfma_f32_16x16x32_bf16 v[54:57], v[162:165], v[220:223], v[54:57]
	v_mfma_f32_16x16x32_bf16 v[30:33], v[166:169], v[192:195], v[30:33]
	v_mfma_f32_16x16x32_bf16 v[30:33], v[172:175], v[196:199], v[30:33]
	v_mfma_f32_16x16x32_bf16 v[14:17], v[176:179], v[192:195], v[14:17]
	v_mfma_f32_16x16x32_bf16 v[14:17], v[188:191], v[196:199], v[14:17]
	v_mfma_f32_16x16x32_bf16 v[26:29], v[166:169], v[200:203], v[26:29]
	v_mfma_f32_16x16x32_bf16 v[26:29], v[172:175], v[204:207], v[26:29]
	v_mfma_f32_16x16x32_bf16 v[10:13], v[176:179], v[200:203], v[10:13]
	v_mfma_f32_16x16x32_bf16 v[10:13], v[188:191], v[204:207], v[10:13]
	v_mfma_f32_16x16x32_bf16 v[22:25], v[166:169], v[208:211], v[22:25]
	v_mfma_f32_16x16x32_bf16 v[22:25], v[172:175], v[212:215], v[22:25]
	v_mfma_f32_16x16x32_bf16 v[6:9], v[176:179], v[208:211], v[6:9]
	v_mfma_f32_16x16x32_bf16 v[6:9], v[188:191], v[212:215], v[6:9]
	v_mfma_f32_16x16x32_bf16 v[18:21], v[166:169], v[216:219], v[18:21]
	v_mfma_f32_16x16x32_bf16 v[18:21], v[172:175], v[220:223], v[18:21]
	v_mfma_f32_16x16x32_bf16 v[2:5], v[176:179], v[216:219], v[2:5]
	v_mfma_f32_16x16x32_bf16 v[2:5], v[188:191], v[220:223], v[2:5]
	s_barrier
; #define PG8_STAGE(bufoff, gbase, voff) do { _Pragma("unroll") for (int _i = 0; _i < 2; ++_i) \
;         __builtin_amdgcn_global_load_lds((const unsigned*)((const char*)(gbase) + (voff)[_i]), (PG8_LAS unsigned*)(lds + (bufoff) + ldsw + _i * 8192), 16, 0, 0); } while (0)
; #define PG8_LDA(dst, b, h) do { _Pragma("unroll") for (int m = 0; m < 4; ++m) _Pragma("unroll") for (int k = 0; k < 2; ++k) dst[m][k] = *(const PG8_LAS bf16x8*)(lds + PG8_SA(b, h) + aoff + m * 2048 + k * 1024); } while (0)
; #define PG8_LDB(dst, b, h) do { _Pragma("unroll") for (int n = 0; n < 2; ++n) _Pragma("unroll") for (int k = 0; k < 2; ++k) dst[n][k] = *(const PG8_LAS bf16x8*)(lds + PG8_SB(b, h) + boff + n * 2048 + k * 1024); } while (0)
; #define PG8_WAIT_V(n) asm volatile("s_waitcnt vmcnt(" #n ")" ::: "memory")
; #define PG8_WAIT_L(n) asm volatile("s_waitcnt lgkmcnt(" #n ")" ::: "memory")
; #define PG8_BAR __builtin_amdgcn_s_barrier()
; #define PG8_SCHED __builtin_amdgcn_sched_barrier(0)
;     ...
;         for (int t = 0; t < nt * KREP; t += 2) {
;             const bool last = (t == nt * KREP - 2);
;     ...
;             PG8_LDB(B0, 1, 0); PG8_LDB(B1, 1, 1); PG8_SCHED; PG8_LDA(At, 1, 0); PG8_STAGE(PG8_SA(0, 1), a2 + hstep, voffA);
;             PG8_WAIT_V(8); PG8_WAIT_L(0); PG8_BAR; PG8_MMA(0, 0, At, B0); PG8_MMA(0, 1, At, B1); PG8_BAR; PG8_SCHED;
;             PG8_LDA(At, 1, 1); PG8_STAGE(PG8_SB(1, 0), b3, voffB); PG8_STAGE(PG8_SB(1, 1), b3 + hstep, voffB); PG8_STAGE(PG8_SA(1, 0), a3, voffA);
;             PG8_WAIT_V(8); PG8_WAIT_L(0); PG8_BAR; PG8_MMA(1, 0, At, B0); PG8_MMA(1, 1, At, B1); PG8_BAR; PG8_SCHED;
	s_setprio 0
	s_add_i32 s83, 0, 0x18000
	s_add_i32 s84, 0, 0x1c000
	ds_read_b128 v[150:153], v180 offset:32768
	ds_read_b128 v[154:157], v180 offset:33792
	ds_read_b128 v[158:161], v180 offset:34816
	ds_read_b128 v[162:165], v180 offset:35840
	ds_read_b128 v[166:169], v180 offset:49152
	ds_read_b128 v[172:175], v180 offset:50176
	ds_read_b128 v[176:179], v180 offset:51200
	ds_read_b128 v[188:191], v180 offset:52224
	s_add_u32 s0, s78, 0x80000
	s_addc_u32 s1, s79, 0
	s_mov_b32 m0, s43
	ds_read_b128 v[192:195], v148 offset:32768
	ds_read_b128 v[196:199], v148 offset:33792
	ds_read_b128 v[200:203], v148 offset:34816
	ds_read_b128 v[204:207], v148 offset:35840
	ds_read_b128 v[208:211], v148 offset:36864
	ds_read_b128 v[212:215], v148 offset:37888
	ds_read_b128 v[216:219], v148 offset:38912
	ds_read_b128 v[220:223], v148 offset:39936
	global_load_lds_dwordx4 v130, s[0:1]
	s_mov_b32 m0, s44
	s_nop 0
	global_load_lds_dwordx4 v134, s[0:1]
	s_waitcnt vmcnt(8)
	s_waitcnt lgkmcnt(0)
	s_setprio 1
	s_barrier
	v_mfma_f32_16x16x32_bf16 v[126:129], v[150:153], v[192:195], v[126:129]
	v_mfma_f32_16x16x32_bf16 v[126:129], v[154:157], v[196:199], v[126:129]
	v_mfma_f32_16x16x32_bf16 v[110:113], v[158:161], v[192:195], v[110:113]
	v_mfma_f32_16x16x32_bf16 v[110:113], v[162:165], v[196:199], v[110:113]
	v_mfma_f32_16x16x32_bf16 v[122:125], v[150:153], v[200:203], v[122:125]
	v_mfma_f32_16x16x32_bf16 v[122:125], v[154:157], v[204:207], v[122:125]
	v_mfma_f32_16x16x32_bf16 v[106:109], v[158:161], v[200:203], v[106:109]
	v_mfma_f32_16x16x32_bf16 v[106:109], v[162:165], v[204:207], v[106:109]
	v_mfma_f32_16x16x32_bf16 v[118:121], v[150:153], v[208:211], v[118:121]
	v_mfma_f32_16x16x32_bf16 v[118:121], v[154:157], v[212:215], v[118:121]
	v_mfma_f32_16x16x32_bf16 v[102:105], v[158:161], v[208:211], v[102:105]
	v_mfma_f32_16x16x32_bf16 v[102:105], v[162:165], v[212:215], v[102:105]
	v_mfma_f32_16x16x32_bf16 v[114:117], v[150:153], v[216:219], v[114:117]
	v_mfma_f32_16x16x32_bf16 v[114:117], v[154:157], v[220:223], v[114:117]
	v_mfma_f32_16x16x32_bf16 v[98:101], v[158:161], v[216:219], v[98:101]
	v_mfma_f32_16x16x32_bf16 v[98:101], v[162:165], v[220:223], v[98:101]
	v_mfma_f32_16x16x32_bf16 v[70:73], v[166:169], v[192:195], v[70:73]
	v_mfma_f32_16x16x32_bf16 v[70:73], v[172:175], v[196:199], v[70:73]
	v_mfma_f32_16x16x32_bf16 v[50:53], v[176:179], v[192:195], v[50:53]
	v_mfma_f32_16x16x32_bf16 v[50:53], v[188:191], v[196:199], v[50:53]
	v_mfma_f32_16x16x32_bf16 v[66:69], v[166:169], v[200:203], v[66:69]
	v_mfma_f32_16x16x32_bf16 v[66:69], v[172:175], v[204:207], v[66:69]
	v_mfma_f32_16x16x32_bf16 v[42:45], v[176:179], v[200:203], v[42:45]
	v_mfma_f32_16x16x32_bf16 v[42:45], v[188:191], v[204:207], v[42:45]
	v_mfma_f32_16x16x32_bf16 v[58:61], v[166:169], v[208:211], v[58:61]
	v_mfma_f32_16x16x32_bf16 v[58:61], v[172:175], v[212:215], v[58:61]
	v_mfma_f32_16x16x32_bf16 v[38:41], v[176:179], v[208:211], v[38:41]
	v_mfma_f32_16x16x32_bf16 v[38:41], v[188:191], v[212:215], v[38:41]
	v_mfma_f32_16x16x32_bf16 v[46:49], v[166:169], v[216:219], v[46:49]
	v_mfma_f32_16x16x32_bf16 v[46:49], v[172:175], v[220:223], v[46:49]
	v_mfma_f32_16x16x32_bf16 v[34:37], v[176:179], v[216:219], v[34:37]
	v_mfma_f32_16x16x32_bf16 v[34:37], v[188:191], v[220:223], v[34:37]
	s_barrier
	s_setprio 0
	s_add_i32 s0, s83, s20
	s_mov_b32 m0, s0
	ds_read_b128 v[192:195], v148 offset:49152
	ds_read_b128 v[196:199], v148 offset:50176
	ds_read_b128 v[200:203], v148 offset:51200
	ds_read_b128 v[204:207], v148 offset:52224
	ds_read_b128 v[208:211], v148 offset:53248
	ds_read_b128 v[212:215], v148 offset:54272
	ds_read_b128 v[216:219], v148 offset:55296
	ds_read_b128 v[220:223], v148 offset:56320
	s_add_u32 s100, s76, 0x80
	s_addc_u32 s101, s77, 0
	global_load_lds_dwordx4 v132, s[100:101]
	s_add_i32 m0, s0, 0x2000
	s_add_u32 s0, s76, 0x80080
	s_addc_u32 s1, s77, 0
	s_add_i32 s76, s84, s20
	global_load_lds_dwordx4 v136, s[100:101]
	s_mov_b32 m0, s76
	s_nop 0
	global_load_lds_dwordx4 v132, s[0:1]
	s_add_i32 m0, s76, 0x2000
	s_nop 0
	global_load_lds_dwordx4 v136, s[0:1]
	s_mov_b32 m0, s48
	s_nop 0
	s_add_u32 s100, s78, 0x80
	s_addc_u32 s101, s79, 0
	global_load_lds_dwordx4 v130, s[100:101]
	s_mov_b32 m0, s49
	s_nop 0
	global_load_lds_dwordx4 v134, s[100:101]
	s_waitcnt vmcnt(8)
	s_waitcnt lgkmcnt(0)
	s_setprio 1
	s_barrier
	v_mfma_f32_16x16x32_bf16 v[94:97], v[150:153], v[192:195], v[94:97]
	v_mfma_f32_16x16x32_bf16 v[94:97], v[154:157], v[196:199], v[94:97]
	v_mfma_f32_16x16x32_bf16 v[78:81], v[158:161], v[192:195], v[78:81]
	v_mfma_f32_16x16x32_bf16 v[78:81], v[162:165], v[196:199], v[78:81]
	v_mfma_f32_16x16x32_bf16 v[90:93], v[150:153], v[200:203], v[90:93]
	v_mfma_f32_16x16x32_bf16 v[90:93], v[154:157], v[204:207], v[90:93]
	v_mfma_f32_16x16x32_bf16 v[74:77], v[158:161], v[200:203], v[74:77]
	v_mfma_f32_16x16x32_bf16 v[74:77], v[162:165], v[204:207], v[74:77]
	v_mfma_f32_16x16x32_bf16 v[86:89], v[150:153], v[208:211], v[86:89]
	v_mfma_f32_16x16x32_bf16 v[86:89], v[154:157], v[212:215], v[86:89]
	v_mfma_f32_16x16x32_bf16 v[62:65], v[158:161], v[208:211], v[62:65]
	v_mfma_f32_16x16x32_bf16 v[62:65], v[162:165], v[212:215], v[62:65]
	v_mfma_f32_16x16x32_bf16 v[82:85], v[150:153], v[216:219], v[82:85]
	v_mfma_f32_16x16x32_bf16 v[82:85], v[154:157], v[220:223], v[82:85]
	v_mfma_f32_16x16x32_bf16 v[54:57], v[158:161], v[216:219], v[54:57]
	v_mfma_f32_16x16x32_bf16 v[54:57], v[162:165], v[220:223], v[54:57]
	v_mfma_f32_16x16x32_bf16 v[30:33], v[166:169], v[192:195], v[30:33]
	v_mfma_f32_16x16x32_bf16 v[30:33], v[172:175], v[196:199], v[30:33]
	v_mfma_f32_16x16x32_bf16 v[14:17], v[176:179], v[192:195], v[14:17]
	v_mfma_f32_16x16x32_bf16 v[14:17], v[188:191], v[196:199], v[14:17]
	v_mfma_f32_16x16x32_bf16 v[26:29], v[166:169], v[200:203], v[26:29]
	v_mfma_f32_16x16x32_bf16 v[26:29], v[172:175], v[204:207], v[26:29]
	v_mfma_f32_16x16x32_bf16 v[10:13], v[176:179], v[200:203], v[10:13]
	v_mfma_f32_16x16x32_bf16 v[10:13], v[188:191], v[204:207], v[10:13]
	v_mfma_f32_16x16x32_bf16 v[22:25], v[166:169], v[208:211], v[22:25]
	v_mfma_f32_16x16x32_bf16 v[22:25], v[172:175], v[212:215], v[22:25]
	v_mfma_f32_16x16x32_bf16 v[6:9], v[176:179], v[208:211], v[6:9]
	v_mfma_f32_16x16x32_bf16 v[6:9], v[188:191], v[212:215], v[6:9]
	v_mfma_f32_16x16x32_bf16 v[18:21], v[166:169], v[216:219], v[18:21]
	v_mfma_f32_16x16x32_bf16 v[18:21], v[172:175], v[220:223], v[18:21]
	v_mfma_f32_16x16x32_bf16 v[2:5], v[176:179], v[216:219], v[2:5]
	v_mfma_f32_16x16x32_bf16 v[2:5], v[188:191], v[220:223], v[2:5]
	s_barrier
	s_setprio 0
	s_add_i32 s82, s82, 2
	s_add_u32 s74, s74, 0x100
	s_addc_u32 s75, s75, 0
	s_add_u32 s80, s80, 0x100
	s_addc_u32 s81, s81, 0
	s_cmp_gt_u32 s82, 29
	s_cbranch_scc0 .LBB0_596
	s_and_b64 vcc, exec, s[62:63]
	s_cbranch_vccz .LBB0_599
	s_barrier

; #define PG8_STAGE(bufoff, gbase, voff) do { _Pragma("unroll") for (int _i = 0; _i < 2; ++_i) \
;         __builtin_amdgcn_global_load_lds((const unsigned*)((const char*)(gbase) + (voff)[_i]), (PG8_LAS unsigned*)(lds + (bufoff) + ldsw + _i * 8192), 16, 0, 0); } while (0)
; #define PG8_LDA(dst, b, h) do { _Pragma("unroll") for (int m = 0; m < 4; ++m) _Pragma("unroll") for (int k = 0; k < 2; ++k) dst[m][k] = *(const PG8_LAS bf16x8*)(lds + PG8_SA(b, h) + aoff + m * 2048 + k * 1024); } while (0)
; #define PG8_LDB(dst, b, h) do { _Pragma("unroll") for (int n = 0; n < 2; ++n) _Pragma("unroll") for (int k = 0; k < 2; ++k) dst[n][k] = *(const PG8_LAS bf16x8*)(lds + PG8_SB(b, h) + boff + n * 2048 + k * 1024); } while (0)
; #define PG8_WAIT_L(n) asm volatile("s_waitcnt lgkmcnt(" #n ")" ::: "memory")
; #define PG8_WAIT_V_SEL(sel) asm volatile("s_cmp_eq_u32 %0, 0\n\ts_cbranch_scc1 .Lw8_%=\n\ts_waitcnt vmcnt(22)\n\ts_branch .Lwd_%=\n.Lw8_%=:\n\ts_waitcnt vmcnt(8)\n.Lwd_%=:" :: "s"(sel) : "memory", "scc")
; #define PG8_BAR __builtin_amdgcn_s_barrier()
; #define PG8_SCHED __builtin_amdgcn_sched_barrier(0)
;     ...
;             const bool last = (t == nt * KREP - 2);
;             const int t1w = KREP > 1 ? ((t + 1) & (nt - 1)) : t + 1, t2w = KREP > 1 ? ((t + 2) & (nt - 1)) : t + 2;
;             const char* a1 = cA + (size_t)t1w * kstep;
;             const char* a2 = last ? nA : cA + (size_t)t2w * kstep; const char* b2 = last ? nB : cB + (size_t)t2w * kstep;
;             const char* a3 = a2 + kstep; const char* b3 = b2 + kstep;
;             if (last && has_next) S.a_ready(nxt);
;             const int relax = __builtin_amdgcn_readfirstlane((MK_RELAXW && t == 0 && ui > 0) ? 1 : 0);
;             if constexpr (SP2) {
;             PG8_LDB(B0, 0, 0); PG8_LDB(B1, 0, 1); PG8_SCHED; PG8_LDA(At, 0, 0); PG8_STAGE(PG8_SA(1, 1), a1 + hstep, voffA);
;             PG8_WAIT_V_SEL(relax);
;             PG8_WAIT_L(0); PG8_BAR; PG8_MMA(0, 0, At, B0); PG8_MMA(0, 1, At, B1); PG8_BAR; PG8_SCHED;
;             PG8_LDA(At, 0, 1); PG8_STAGE(PG8_SB(0, 0), b2, voffB); PG8_STAGE(PG8_SB(0, 1), b2 + hstep, voffB); PG8_STAGE(PG8_SA(0, 0), a2, voffA);
;             PG8_WAIT_V_SEL(relax);
;             PG8_WAIT_L(0); PG8_BAR; PG8_MMA(1, 0, At, B0); PG8_MMA(1, 1, At, B1); PG8_BAR; PG8_SCHED;
.LBB0_1170:
	s_add_u32 s0, s78, 0xfff80080
	s_addc_u32 s1, s79, -1
	s_add_i32 s85, 0, 0x10000
	s_cmp_eq_u32 s84, 28
	s_cselect_b32 s83, s40, s1
	s_cselect_b32 s82, s41, s0
	s_cselect_b32 s81, s67, s77
	s_cselect_b32 s80, s69, s75
	s_add_i32 s86, 0, 0x14000
	ds_read_b128 v[90:93], v184
	ds_read_b128 v[94:97], v184 offset:1024
	ds_read_b128 v[98:101], v184 offset:2048
	ds_read_b128 v[102:105], v184 offset:3072
	ds_read_b128 v[146:149], v184 offset:16384
	ds_read_b128 v[150:153], v184 offset:17408
	ds_read_b128 v[154:157], v184 offset:18432
	ds_read_b128 v[158:161], v184 offset:19456
	s_add_i32 m0, s45, 0xc000
	ds_read_b128 v[162:165], v227
	ds_read_b128 v[166:169], v227 offset:1024
	ds_read_b128 v[188:191], v227 offset:2048
	ds_read_b128 v[192:195], v227 offset:3072
	ds_read_b128 v[196:199], v227 offset:4096
	ds_read_b128 v[200:203], v227 offset:5120
	ds_read_b128 v[204:207], v227 offset:6144
	ds_read_b128 v[208:211], v227 offset:7168
	global_load_lds_dwordx4 v178, s[78:79]
	s_add_i32 m0, s45, 0xe000
	s_nop 0
	global_load_lds_dwordx4 v180, s[78:79]
	s_waitcnt vmcnt(8)
	s_waitcnt lgkmcnt(0)
	s_setprio 1
	s_barrier
	v_mfma_f32_16x16x32_bf16 v[142:145], v[90:93], v[162:165], v[142:145]
	v_mfma_f32_16x16x32_bf16 v[142:145], v[94:97], v[166:169], v[142:145]
	v_mfma_f32_16x16x32_bf16 v[138:141], v[98:101], v[162:165], v[138:141]
	v_mfma_f32_16x16x32_bf16 v[138:141], v[102:105], v[166:169], v[138:141]
	v_mfma_f32_16x16x32_bf16 v[126:129], v[90:93], v[188:191], v[126:129]
	v_mfma_f32_16x16x32_bf16 v[126:129], v[94:97], v[192:195], v[126:129]
	v_mfma_f32_16x16x32_bf16 v[122:125], v[98:101], v[188:191], v[122:125]
	v_mfma_f32_16x16x32_bf16 v[122:125], v[102:105], v[192:195], v[122:125]
	v_mfma_f32_16x16x32_bf16 v[110:113], v[90:93], v[196:199], v[110:113]
	v_mfma_f32_16x16x32_bf16 v[110:113], v[94:97], v[200:203], v[110:113]
	v_mfma_f32_16x16x32_bf16 v[106:109], v[98:101], v[196:199], v[106:109]
	v_mfma_f32_16x16x32_bf16 v[106:109], v[102:105], v[200:203], v[106:109]
	v_mfma_f32_16x16x32_bf16 v[78:81], v[90:93], v[204:207], v[78:81]
	v_mfma_f32_16x16x32_bf16 v[78:81], v[94:97], v[208:211], v[78:81]
	v_mfma_f32_16x16x32_bf16 v[74:77], v[98:101], v[204:207], v[74:77]
	v_mfma_f32_16x16x32_bf16 v[74:77], v[102:105], v[208:211], v[74:77]
	v_mfma_f32_16x16x32_bf16 v[134:137], v[146:149], v[162:165], v[134:137]
	v_mfma_f32_16x16x32_bf16 v[134:137], v[150:153], v[166:169], v[134:137]
	v_mfma_f32_16x16x32_bf16 v[130:133], v[154:157], v[162:165], v[130:133]
	v_mfma_f32_16x16x32_bf16 v[130:133], v[158:161], v[166:169], v[130:133]
	v_mfma_f32_16x16x32_bf16 v[118:121], v[146:149], v[188:191], v[118:121]
	v_mfma_f32_16x16x32_bf16 v[118:121], v[150:153], v[192:195], v[118:121]
	v_mfma_f32_16x16x32_bf16 v[114:117], v[154:157], v[188:191], v[114:117]
	v_mfma_f32_16x16x32_bf16 v[114:117], v[158:161], v[192:195], v[114:117]
	v_mfma_f32_16x16x32_bf16 v[86:89], v[146:149], v[196:199], v[86:89]
	v_mfma_f32_16x16x32_bf16 v[86:89], v[150:153], v[200:203], v[86:89]
	v_mfma_f32_16x16x32_bf16 v[82:85], v[154:157], v[196:199], v[82:85]
	v_mfma_f32_16x16x32_bf16 v[82:85], v[158:161], v[200:203], v[82:85]
	v_mfma_f32_16x16x32_bf16 v[70:73], v[146:149], v[204:207], v[70:73]
	v_mfma_f32_16x16x32_bf16 v[70:73], v[150:153], v[208:211], v[70:73]
	v_mfma_f32_16x16x32_bf16 v[66:69], v[154:157], v[204:207], v[66:69]
	v_mfma_f32_16x16x32_bf16 v[66:69], v[158:161], v[208:211], v[66:69]
	s_barrier
	s_setprio 0
	s_add_i32 s0, s85, s33
	s_mov_b32 m0, s0
	ds_read_b128 v[162:165], v227 offset:16384
	ds_read_b128 v[166:169], v227 offset:17408
	ds_read_b128 v[188:191], v227 offset:18432
	ds_read_b128 v[192:195], v227 offset:19456
	ds_read_b128 v[196:199], v227 offset:20480
	ds_read_b128 v[200:203], v227 offset:21504
	ds_read_b128 v[204:207], v227 offset:22528
	ds_read_b128 v[208:211], v227 offset:23552
	global_load_lds_dwordx4 v182, s[80:81]
	s_add_i32 m0, s0, 0x2000
	s_add_u32 s0, s80, 0x80000
	s_addc_u32 s1, s81, 0
	s_add_i32 s85, s86, s33
	global_load_lds_dwordx4 v176, s[80:81]
	s_mov_b32 m0, s85
	s_nop 0
	global_load_lds_dwordx4 v182, s[0:1]
	s_add_i32 m0, s85, 0x2000
	s_nop 0
	global_load_lds_dwordx4 v176, s[0:1]
	s_mov_b32 m0, s45
	s_nop 0
	global_load_lds_dwordx4 v172, s[82:83]
	s_mov_b32 m0, s46
	s_nop 0
	global_load_lds_dwordx4 v174, s[82:83]
	s_waitcnt vmcnt(8)
	s_waitcnt lgkmcnt(0)
	s_setprio 1
	s_barrier
	v_mfma_f32_16x16x32_bf16 v[62:65], v[90:93], v[162:165], v[62:65]
	v_mfma_f32_16x16x32_bf16 v[62:65], v[94:97], v[166:169], v[62:65]
	v_mfma_f32_16x16x32_bf16 v[58:61], v[98:101], v[162:165], v[58:61]
	v_mfma_f32_16x16x32_bf16 v[58:61], v[102:105], v[166:169], v[58:61]
	v_mfma_f32_16x16x32_bf16 v[46:49], v[90:93], v[188:191], v[46:49]
	v_mfma_f32_16x16x32_bf16 v[46:49], v[94:97], v[192:195], v[46:49]
	v_mfma_f32_16x16x32_bf16 v[42:45], v[98:101], v[188:191], v[42:45]
	v_mfma_f32_16x16x32_bf16 v[42:45], v[102:105], v[192:195], v[42:45]
	v_mfma_f32_16x16x32_bf16 v[30:33], v[90:93], v[196:199], v[30:33]
	v_mfma_f32_16x16x32_bf16 v[30:33], v[94:97], v[200:203], v[30:33]
	v_mfma_f32_16x16x32_bf16 v[26:29], v[98:101], v[196:199], v[26:29]
	v_mfma_f32_16x16x32_bf16 v[26:29], v[102:105], v[200:203], v[26:29]
	v_mfma_f32_16x16x32_bf16 v[14:17], v[90:93], v[204:207], v[14:17]
	v_mfma_f32_16x16x32_bf16 v[14:17], v[94:97], v[208:211], v[14:17]
	v_mfma_f32_16x16x32_bf16 v[10:13], v[98:101], v[204:207], v[10:13]
	v_mfma_f32_16x16x32_bf16 v[10:13], v[102:105], v[208:211], v[10:13]
	v_mfma_f32_16x16x32_bf16 v[54:57], v[146:149], v[162:165], v[54:57]
	v_mfma_f32_16x16x32_bf16 v[54:57], v[150:153], v[166:169], v[54:57]
	v_mfma_f32_16x16x32_bf16 v[50:53], v[154:157], v[162:165], v[50:53]
	v_mfma_f32_16x16x32_bf16 v[50:53], v[158:161], v[166:169], v[50:53]
	v_mfma_f32_16x16x32_bf16 v[38:41], v[146:149], v[188:191], v[38:41]
	v_mfma_f32_16x16x32_bf16 v[38:41], v[150:153], v[192:195], v[38:41]
	v_mfma_f32_16x16x32_bf16 v[34:37], v[154:157], v[188:191], v[34:37]
	v_mfma_f32_16x16x32_bf16 v[34:37], v[158:161], v[192:195], v[34:37]
	v_mfma_f32_16x16x32_bf16 v[22:25], v[146:149], v[196:199], v[22:25]
	v_mfma_f32_16x16x32_bf16 v[22:25], v[150:153], v[200:203], v[22:25]
	v_mfma_f32_16x16x32_bf16 v[18:21], v[154:157], v[196:199], v[18:21]
	v_mfma_f32_16x16x32_bf16 v[18:21], v[158:161], v[200:203], v[18:21]
	v_mfma_f32_16x16x32_bf16 v[6:9], v[146:149], v[204:207], v[6:9]
	v_mfma_f32_16x16x32_bf16 v[6:9], v[150:153], v[208:211], v[6:9]
	v_mfma_f32_16x16x32_bf16 v[2:5], v[154:157], v[204:207], v[2:5]
	v_mfma_f32_16x16x32_bf16 v[2:5], v[158:161], v[208:211], v[2:5]
	s_barrier
; #define PG8_STAGE(bufoff, gbase, voff) do { _Pragma("unroll") for (int _i = 0; _i < 2; ++_i) \
;         __builtin_amdgcn_global_load_lds((const unsigned*)((const char*)(gbase) + (voff)[_i]), (PG8_LAS unsigned*)(lds + (bufoff) + ldsw + _i * 8192), 16, 0, 0); } while (0)
; #define PG8_LDA(dst, b, h) do { _Pragma("unroll") for (int m = 0; m < 4; ++m) _Pragma("unroll") for (int k = 0; k < 2; ++k) dst[m][k] = *(const PG8_LAS bf16x8*)(lds + PG8_SA(b, h) + aoff + m * 2048 + k * 1024); } while (0)
; #define PG8_LDB(dst, b, h) do { _Pragma("unroll") for (int n = 0; n < 2; ++n) _Pragma("unroll") for (int k = 0; k < 2; ++k) dst[n][k] = *(const PG8_LAS bf16x8*)(lds + PG8_SB(b, h) + boff + n * 2048 + k * 1024); } while (0)
; #define PG8_WAIT_V(n) asm volatile("s_waitcnt vmcnt(" #n ")" ::: "memory")
; #define PG8_WAIT_L(n) asm volatile("s_waitcnt lgkmcnt(" #n ")" ::: "memory")
; #define PG8_BAR __builtin_amdgcn_s_barrier()
; #define PG8_SCHED __builtin_amdgcn_sched_barrier(0)
;     ...
;             PG8_LDB(B0, 1, 0); PG8_LDB(B1, 1, 1); PG8_SCHED; PG8_LDA(At, 1, 0); PG8_STAGE(PG8_SA(0, 1), a2 + hstep, voffA);
;             PG8_WAIT_V(8); PG8_WAIT_L(0); PG8_BAR; PG8_MMA(0, 0, At, B0); PG8_MMA(0, 1, At, B1); PG8_BAR; PG8_SCHED;
;             PG8_LDA(At, 1, 1); PG8_STAGE(PG8_SB(1, 0), b3, voffB); PG8_STAGE(PG8_SB(1, 1), b3 + hstep, voffB); PG8_STAGE(PG8_SA(1, 0), a3, voffA);
;             PG8_WAIT_V(8); PG8_WAIT_L(0); PG8_BAR; PG8_MMA(1, 0, At, B0); PG8_MMA(1, 1, At, B1); PG8_BAR; PG8_SCHED;
	s_setprio 0
	s_add_i32 s85, 0, 0x18000
	s_add_i32 s86, 0, 0x1c000
	ds_read_b128 v[90:93], v184 offset:32768
	ds_read_b128 v[94:97], v184 offset:33792
	ds_read_b128 v[98:101], v184 offset:34816
	ds_read_b128 v[102:105], v184 offset:35840
	ds_read_b128 v[146:149], v184 offset:49152
	ds_read_b128 v[150:153], v184 offset:50176
	ds_read_b128 v[154:157], v184 offset:51200
	ds_read_b128 v[158:161], v184 offset:52224
	s_add_u32 s0, s82, 0x80000
	s_addc_u32 s1, s83, 0
	s_mov_b32 m0, s47
	ds_read_b128 v[162:165], v227 offset:32768
	ds_read_b128 v[166:169], v227 offset:33792
	ds_read_b128 v[188:191], v227 offset:34816
	ds_read_b128 v[192:195], v227 offset:35840
	ds_read_b128 v[196:199], v227 offset:36864
	ds_read_b128 v[200:203], v227 offset:37888
	ds_read_b128 v[204:207], v227 offset:38912
	ds_read_b128 v[208:211], v227 offset:39936
	global_load_lds_dwordx4 v172, s[0:1]
	s_mov_b32 m0, s48
	s_nop 0
	global_load_lds_dwordx4 v174, s[0:1]
	s_waitcnt vmcnt(8)
	s_waitcnt lgkmcnt(0)
	s_setprio 1
	s_barrier
	v_mfma_f32_16x16x32_bf16 v[142:145], v[90:93], v[162:165], v[142:145]
	v_mfma_f32_16x16x32_bf16 v[142:145], v[94:97], v[166:169], v[142:145]
	v_mfma_f32_16x16x32_bf16 v[138:141], v[98:101], v[162:165], v[138:141]
	v_mfma_f32_16x16x32_bf16 v[138:141], v[102:105], v[166:169], v[138:141]
	v_mfma_f32_16x16x32_bf16 v[126:129], v[90:93], v[188:191], v[126:129]
	v_mfma_f32_16x16x32_bf16 v[126:129], v[94:97], v[192:195], v[126:129]
	v_mfma_f32_16x16x32_bf16 v[122:125], v[98:101], v[188:191], v[122:125]
	v_mfma_f32_16x16x32_bf16 v[122:125], v[102:105], v[192:195], v[122:125]
	v_mfma_f32_16x16x32_bf16 v[110:113], v[90:93], v[196:199], v[110:113]
	v_mfma_f32_16x16x32_bf16 v[110:113], v[94:97], v[200:203], v[110:113]
	v_mfma_f32_16x16x32_bf16 v[106:109], v[98:101], v[196:199], v[106:109]
	v_mfma_f32_16x16x32_bf16 v[106:109], v[102:105], v[200:203], v[106:109]
	v_mfma_f32_16x16x32_bf16 v[78:81], v[90:93], v[204:207], v[78:81]
	v_mfma_f32_16x16x32_bf16 v[78:81], v[94:97], v[208:211], v[78:81]
	v_mfma_f32_16x16x32_bf16 v[74:77], v[98:101], v[204:207], v[74:77]
	v_mfma_f32_16x16x32_bf16 v[74:77], v[102:105], v[208:211], v[74:77]
	v_mfma_f32_16x16x32_bf16 v[134:137], v[146:149], v[162:165], v[134:137]
	v_mfma_f32_16x16x32_bf16 v[134:137], v[150:153], v[166:169], v[134:137]
	v_mfma_f32_16x16x32_bf16 v[130:133], v[154:157], v[162:165], v[130:133]
	v_mfma_f32_16x16x32_bf16 v[130:133], v[158:161], v[166:169], v[130:133]
	v_mfma_f32_16x16x32_bf16 v[118:121], v[146:149], v[188:191], v[118:121]
	v_mfma_f32_16x16x32_bf16 v[118:121], v[150:153], v[192:195], v[118:121]
	v_mfma_f32_16x16x32_bf16 v[114:117], v[154:157], v[188:191], v[114:117]
	v_mfma_f32_16x16x32_bf16 v[114:117], v[158:161], v[192:195], v[114:117]
	v_mfma_f32_16x16x32_bf16 v[86:89], v[146:149], v[196:199], v[86:89]
	v_mfma_f32_16x16x32_bf16 v[86:89], v[150:153], v[200:203], v[86:89]
	v_mfma_f32_16x16x32_bf16 v[82:85], v[154:157], v[196:199], v[82:85]
	v_mfma_f32_16x16x32_bf16 v[82:85], v[158:161], v[200:203], v[82:85]
	v_mfma_f32_16x16x32_bf16 v[70:73], v[146:149], v[204:207], v[70:73]
	v_mfma_f32_16x16x32_bf16 v[70:73], v[150:153], v[208:211], v[70:73]
	v_mfma_f32_16x16x32_bf16 v[66:69], v[154:157], v[204:207], v[66:69]
	v_mfma_f32_16x16x32_bf16 v[66:69], v[158:161], v[208:211], v[66:69]
	s_barrier
	s_setprio 0
	s_add_i32 s0, s85, s33
	s_mov_b32 m0, s0
	ds_read_b128 v[162:165], v227 offset:49152
	ds_read_b128 v[166:169], v227 offset:50176
	ds_read_b128 v[188:191], v227 offset:51200
	ds_read_b128 v[192:195], v227 offset:52224
	ds_read_b128 v[196:199], v227 offset:53248
	ds_read_b128 v[200:203], v227 offset:54272
	ds_read_b128 v[204:207], v227 offset:55296
	ds_read_b128 v[208:211], v227 offset:56320
	s_add_u32 s100, s80, 0x80
	s_addc_u32 s101, s81, 0
	global_load_lds_dwordx4 v182, s[100:101]
	s_add_i32 m0, s0, 0x2000
	s_add_u32 s0, s80, 0x80080
	s_addc_u32 s1, s81, 0
	s_add_i32 s80, s86, s33
	global_load_lds_dwordx4 v176, s[100:101]
	s_mov_b32 m0, s80
	s_nop 0
	global_load_lds_dwordx4 v182, s[0:1]
	s_add_i32 m0, s80, 0x2000
	s_nop 0
	global_load_lds_dwordx4 v176, s[0:1]
	s_mov_b32 m0, s50
	s_nop 0
	s_add_u32 s100, s82, 0x80
	s_addc_u32 s101, s83, 0
	global_load_lds_dwordx4 v172, s[100:101]
	s_mov_b32 m0, s51
	s_nop 0
	global_load_lds_dwordx4 v174, s[100:101]
	s_waitcnt vmcnt(8)
	s_waitcnt lgkmcnt(0)
	s_setprio 1
	s_barrier
	v_mfma_f32_16x16x32_bf16 v[62:65], v[90:93], v[162:165], v[62:65]
	v_mfma_f32_16x16x32_bf16 v[62:65], v[94:97], v[166:169], v[62:65]
	v_mfma_f32_16x16x32_bf16 v[58:61], v[98:101], v[162:165], v[58:61]
	v_mfma_f32_16x16x32_bf16 v[58:61], v[102:105], v[166:169], v[58:61]
	v_mfma_f32_16x16x32_bf16 v[46:49], v[90:93], v[188:191], v[46:49]
	v_mfma_f32_16x16x32_bf16 v[46:49], v[94:97], v[192:195], v[46:49]
	v_mfma_f32_16x16x32_bf16 v[42:45], v[98:101], v[188:191], v[42:45]
	v_mfma_f32_16x16x32_bf16 v[42:45], v[102:105], v[192:195], v[42:45]
	v_mfma_f32_16x16x32_bf16 v[30:33], v[90:93], v[196:199], v[30:33]
	v_mfma_f32_16x16x32_bf16 v[30:33], v[94:97], v[200:203], v[30:33]
	v_mfma_f32_16x16x32_bf16 v[26:29], v[98:101], v[196:199], v[26:29]
	v_mfma_f32_16x16x32_bf16 v[26:29], v[102:105], v[200:203], v[26:29]
	v_mfma_f32_16x16x32_bf16 v[14:17], v[90:93], v[204:207], v[14:17]
	v_mfma_f32_16x16x32_bf16 v[14:17], v[94:97], v[208:211], v[14:17]
	v_mfma_f32_16x16x32_bf16 v[10:13], v[98:101], v[204:207], v[10:13]
	v_mfma_f32_16x16x32_bf16 v[10:13], v[102:105], v[208:211], v[10:13]
	v_mfma_f32_16x16x32_bf16 v[54:57], v[146:149], v[162:165], v[54:57]
	v_mfma_f32_16x16x32_bf16 v[54:57], v[150:153], v[166:169], v[54:57]
	v_mfma_f32_16x16x32_bf16 v[50:53], v[154:157], v[162:165], v[50:53]
	v_mfma_f32_16x16x32_bf16 v[50:53], v[158:161], v[166:169], v[50:53]
	v_mfma_f32_16x16x32_bf16 v[38:41], v[146:149], v[188:191], v[38:41]
	v_mfma_f32_16x16x32_bf16 v[38:41], v[150:153], v[192:195], v[38:41]
	v_mfma_f32_16x16x32_bf16 v[34:37], v[154:157], v[188:191], v[34:37]
	v_mfma_f32_16x16x32_bf16 v[34:37], v[158:161], v[192:195], v[34:37]
	v_mfma_f32_16x16x32_bf16 v[22:25], v[146:149], v[196:199], v[22:25]
	v_mfma_f32_16x16x32_bf16 v[22:25], v[150:153], v[200:203], v[22:25]
	v_mfma_f32_16x16x32_bf16 v[18:21], v[154:157], v[196:199], v[18:21]
	v_mfma_f32_16x16x32_bf16 v[18:21], v[158:161], v[200:203], v[18:21]
	v_mfma_f32_16x16x32_bf16 v[6:9], v[146:149], v[204:207], v[6:9]
	v_mfma_f32_16x16x32_bf16 v[6:9], v[150:153], v[208:211], v[6:9]
	v_mfma_f32_16x16x32_bf16 v[2:5], v[154:157], v[204:207], v[2:5]
	v_mfma_f32_16x16x32_bf16 v[2:5], v[158:161], v[208:211], v[2:5]
	s_barrier
	s_setprio 0
	s_add_i32 s84, s84, 2
	s_add_u32 s78, s78, 0x100
	s_addc_u32 s79, s79, 0
	s_add_u32 s75, s75, 0x100
	s_addc_u32 s77, s77, 0
	s_cmp_gt_u32 s84, 29
	s_cbranch_scc0 .LBB0_1170
	s_and_b64 vcc, exec, s[64:65]
	s_cbranch_vccz .LBB0_1173
	s_barrier

; #define PG8_STAGE(bufoff, gbase, voff) do { _Pragma("unroll") for (int _i = 0; _i < 2; ++_i) \
;         __builtin_amdgcn_global_load_lds((const unsigned*)((const char*)(gbase) + (voff)[_i]), (PG8_LAS unsigned*)(lds + (bufoff) + ldsw + _i * 8192), 16, 0, 0); } while (0)
; #define PG8_LDA(dst, b, h) do { _Pragma("unroll") for (int m = 0; m < 4; ++m) _Pragma("unroll") for (int k = 0; k < 2; ++k) dst[m][k] = *(const PG8_LAS bf16x8*)(lds + PG8_SA(b, h) + aoff + m * 2048 + k * 1024); } while (0)
; #define PG8_LDB(dst, b, h) do { _Pragma("unroll") for (int n = 0; n < 2; ++n) _Pragma("unroll") for (int k = 0; k < 2; ++k) dst[n][k] = *(const PG8_LAS bf16x8*)(lds + PG8_SB(b, h) + boff + n * 2048 + k * 1024); } while (0)
; #define PG8_WAIT_L(n) asm volatile("s_waitcnt lgkmcnt(" #n ")" ::: "memory")
; #define PG8_WAIT_V_SEL(sel) asm volatile("s_cmp_eq_u32 %0, 0\n\ts_cbranch_scc1 .Lw8_%=\n\ts_waitcnt vmcnt(22)\n\ts_branch .Lwd_%=\n.Lw8_%=:\n\ts_waitcnt vmcnt(8)\n.Lwd_%=:" :: "s"(sel) : "memory", "scc")
; #define PG8_BAR __builtin_amdgcn_s_barrier()
; #define PG8_SCHED __builtin_amdgcn_sched_barrier(0)
;     ...
;             const bool last = (t == nt * KREP - 2);
;             const int t1w = KREP > 1 ? ((t + 1) & (nt - 1)) : t + 1, t2w = KREP > 1 ? ((t + 2) & (nt - 1)) : t + 2;
;             const char* a1 = cA + (size_t)t1w * kstep;
;             const char* a2 = last ? nA : cA + (size_t)t2w * kstep; const char* b2 = last ? nB : cB + (size_t)t2w * kstep;
;             const char* a3 = a2 + kstep; const char* b3 = b2 + kstep;
;             if (last && has_next) S.a_ready(nxt);
;             const int relax = __builtin_amdgcn_readfirstlane((MK_RELAXW && t == 0 && ui > 0) ? 1 : 0);
;             if constexpr (SP2) {
;             PG8_LDB(B0, 0, 0); PG8_LDB(B1, 0, 1); PG8_SCHED; PG8_LDA(At, 0, 0); PG8_STAGE(PG8_SA(1, 1), a1 + hstep, voffA);
;             PG8_WAIT_V_SEL(relax);
;             PG8_WAIT_L(0); PG8_BAR; PG8_MMA(0, 0, At, B0); PG8_MMA(0, 1, At, B1); PG8_BAR; PG8_SCHED;
;             PG8_LDA(At, 0, 1); PG8_STAGE(PG8_SB(0, 0), b2, voffB); PG8_STAGE(PG8_SB(0, 1), b2 + hstep, voffB); PG8_STAGE(PG8_SA(0, 0), a2, voffA);
;             PG8_WAIT_V_SEL(relax);
;             PG8_WAIT_L(0); PG8_BAR; PG8_MMA(1, 0, At, B0); PG8_MMA(1, 1, At, B1); PG8_BAR; PG8_SCHED;
.LBB0_1327:
	s_add_u32 s96, s12, 0x100
	s_addc_u32 s97, s13, 0
	s_add_i32 s51, 0, 0x10000
	s_cmp_eq_u32 s0, 28
	s_cselect_b32 s41, s59, s97
	s_cselect_b32 s40, s64, s96
	s_cselect_b32 vcc_hi, s65, s67
	s_cselect_b32 vcc_lo, s87, s66
	s_add_i32 s19, 0, 0x14000
	ds_read_b128 v[66:69], v200
	ds_read_b128 v[70:73], v200 offset:1024
	ds_read_b128 v[82:85], v200 offset:2048
	ds_read_b128 v[142:145], v200 offset:3072
	ds_read_b128 v[146:149], v200 offset:16384
	ds_read_b128 v[150:153], v200 offset:17408
	ds_read_b128 v[154:157], v200 offset:18432
	ds_read_b128 v[158:161], v200 offset:19456
	s_add_i32 m0, s95, 0xc000
	ds_read_b128 v[162:165], v219
	ds_read_b128 v[166:169], v219 offset:1024
	ds_read_b128 v[170:173], v219 offset:2048
	ds_read_b128 v[174:177], v219 offset:3072
	ds_read_b128 v[178:181], v219 offset:4096
	ds_read_b128 v[184:187], v219 offset:5120
	ds_read_b128 v[220:223], v219 offset:6144
	ds_read_b128 v[224:227], v219 offset:7168
	global_load_lds_dwordx4 v196, s[12:13]
	s_add_i32 m0, s95, 0xe000
	s_nop 0
	global_load_lds_dwordx4 v198, s[12:13]
	s_waitcnt vmcnt(8)
	s_waitcnt lgkmcnt(0)
	s_setprio 1
	s_barrier
	v_mfma_f32_16x16x32_bf16 v[114:117], v[66:69], v[162:165], v[114:117]
	v_mfma_f32_16x16x32_bf16 v[114:117], v[70:73], v[166:169], v[114:117]
	v_mfma_f32_16x16x32_bf16 v[106:109], v[82:85], v[162:165], v[106:109]
	v_mfma_f32_16x16x32_bf16 v[106:109], v[142:145], v[166:169], v[106:109]
	v_mfma_f32_16x16x32_bf16 v[110:113], v[66:69], v[170:173], v[110:113]
	v_mfma_f32_16x16x32_bf16 v[110:113], v[70:73], v[174:177], v[110:113]
	v_mfma_f32_16x16x32_bf16 v[102:105], v[82:85], v[170:173], v[102:105]
	v_mfma_f32_16x16x32_bf16 v[102:105], v[142:145], v[174:177], v[102:105]
	v_mfma_f32_16x16x32_bf16 v[78:81], v[66:69], v[178:181], v[78:81]
	v_mfma_f32_16x16x32_bf16 v[78:81], v[70:73], v[184:187], v[78:81]
	v_mfma_f32_16x16x32_bf16 v[138:141], v[82:85], v[178:181], v[138:141]
	v_mfma_f32_16x16x32_bf16 v[138:141], v[142:145], v[184:187], v[138:141]
	v_mfma_f32_16x16x32_bf16 v[74:77], v[66:69], v[220:223], v[74:77]
	v_mfma_f32_16x16x32_bf16 v[74:77], v[70:73], v[224:227], v[74:77]
	v_mfma_f32_16x16x32_bf16 v[134:137], v[82:85], v[220:223], v[134:137]
	v_mfma_f32_16x16x32_bf16 v[134:137], v[142:145], v[224:227], v[134:137]
	v_mfma_f32_16x16x32_bf16 v[98:101], v[146:149], v[162:165], v[98:101]
	v_mfma_f32_16x16x32_bf16 v[98:101], v[150:153], v[166:169], v[98:101]
	v_mfma_f32_16x16x32_bf16 v[90:93], v[154:157], v[162:165], v[90:93]
	v_mfma_f32_16x16x32_bf16 v[90:93], v[158:161], v[166:169], v[90:93]
	v_mfma_f32_16x16x32_bf16 v[94:97], v[146:149], v[170:173], v[94:97]
	v_mfma_f32_16x16x32_bf16 v[94:97], v[150:153], v[174:177], v[94:97]
	v_mfma_f32_16x16x32_bf16 v[86:89], v[154:157], v[170:173], v[86:89]
	v_mfma_f32_16x16x32_bf16 v[86:89], v[158:161], v[174:177], v[86:89]
	v_mfma_f32_16x16x32_bf16 v[130:133], v[146:149], v[178:181], v[130:133]
	v_mfma_f32_16x16x32_bf16 v[130:133], v[150:153], v[184:187], v[130:133]
	v_mfma_f32_16x16x32_bf16 v[122:125], v[154:157], v[178:181], v[122:125]
	v_mfma_f32_16x16x32_bf16 v[122:125], v[158:161], v[184:187], v[122:125]
	v_mfma_f32_16x16x32_bf16 v[126:129], v[146:149], v[220:223], v[126:129]
	v_mfma_f32_16x16x32_bf16 v[126:129], v[150:153], v[224:227], v[126:129]
	v_mfma_f32_16x16x32_bf16 v[118:121], v[154:157], v[220:223], v[118:121]
	v_mfma_f32_16x16x32_bf16 v[118:121], v[158:161], v[224:227], v[118:121]
	s_barrier
	s_setprio 0
	s_add_i32 s12, s51, s37
	s_mov_b32 m0, s12
	ds_read_b128 v[162:165], v219 offset:16384
	ds_read_b128 v[166:169], v219 offset:17408
	ds_read_b128 v[170:173], v219 offset:18432
	ds_read_b128 v[174:177], v219 offset:19456
	ds_read_b128 v[178:181], v219 offset:20480
	ds_read_b128 v[184:187], v219 offset:21504
	ds_read_b128 v[220:223], v219 offset:22528
	ds_read_b128 v[224:227], v219 offset:23552
	global_load_lds_dwordx4 v182, vcc
	s_add_i32 m0, s12, 0x2000
	s_add_u32 s12, vcc_lo, 0x80000
	s_addc_u32 s13, vcc_hi, 0
	s_add_i32 s19, s19, s37
	global_load_lds_dwordx4 v192, vcc
	s_mov_b32 m0, s19
	s_nop 0
	global_load_lds_dwordx4 v182, s[12:13]
	s_add_i32 m0, s19, 0x2000
	s_nop 0
	global_load_lds_dwordx4 v192, s[12:13]
	s_mov_b32 m0, s95
	s_nop 0
	global_load_lds_dwordx4 v188, s[40:41]
	s_mov_b32 m0, s20
	s_nop 0
	global_load_lds_dwordx4 v190, s[40:41]
	s_waitcnt vmcnt(8)
	s_waitcnt lgkmcnt(0)
	s_setprio 1
	s_barrier
	v_mfma_f32_16x16x32_bf16 v[30:33], v[66:69], v[162:165], v[30:33]
	v_mfma_f32_16x16x32_bf16 v[30:33], v[70:73], v[166:169], v[30:33]
	v_mfma_f32_16x16x32_bf16 v[22:25], v[82:85], v[162:165], v[22:25]
	v_mfma_f32_16x16x32_bf16 v[22:25], v[142:145], v[166:169], v[22:25]
	v_mfma_f32_16x16x32_bf16 v[26:29], v[66:69], v[170:173], v[26:29]
	v_mfma_f32_16x16x32_bf16 v[26:29], v[70:73], v[174:177], v[26:29]
	v_mfma_f32_16x16x32_bf16 v[18:21], v[82:85], v[170:173], v[18:21]
	v_mfma_f32_16x16x32_bf16 v[18:21], v[142:145], v[174:177], v[18:21]
	v_mfma_f32_16x16x32_bf16 v[62:65], v[66:69], v[178:181], v[62:65]
	v_mfma_f32_16x16x32_bf16 v[62:65], v[70:73], v[184:187], v[62:65]
	v_mfma_f32_16x16x32_bf16 v[54:57], v[82:85], v[178:181], v[54:57]
	v_mfma_f32_16x16x32_bf16 v[54:57], v[142:145], v[184:187], v[54:57]
	v_mfma_f32_16x16x32_bf16 v[58:61], v[66:69], v[220:223], v[58:61]
	v_mfma_f32_16x16x32_bf16 v[58:61], v[70:73], v[224:227], v[58:61]
	v_mfma_f32_16x16x32_bf16 v[50:53], v[82:85], v[220:223], v[50:53]
	v_mfma_f32_16x16x32_bf16 v[50:53], v[142:145], v[224:227], v[50:53]
	v_mfma_f32_16x16x32_bf16 v[14:17], v[146:149], v[162:165], v[14:17]
	v_mfma_f32_16x16x32_bf16 v[14:17], v[150:153], v[166:169], v[14:17]
	v_mfma_f32_16x16x32_bf16 v[6:9], v[154:157], v[162:165], v[6:9]
	v_mfma_f32_16x16x32_bf16 v[6:9], v[158:161], v[166:169], v[6:9]
	v_mfma_f32_16x16x32_bf16 v[10:13], v[146:149], v[170:173], v[10:13]
	v_mfma_f32_16x16x32_bf16 v[10:13], v[150:153], v[174:177], v[10:13]
	v_mfma_f32_16x16x32_bf16 v[2:5], v[154:157], v[170:173], v[2:5]
	v_mfma_f32_16x16x32_bf16 v[2:5], v[158:161], v[174:177], v[2:5]
	v_mfma_f32_16x16x32_bf16 v[46:49], v[146:149], v[178:181], v[46:49]
	v_mfma_f32_16x16x32_bf16 v[46:49], v[150:153], v[184:187], v[46:49]
	v_mfma_f32_16x16x32_bf16 v[34:37], v[154:157], v[178:181], v[34:37]
	v_mfma_f32_16x16x32_bf16 v[34:37], v[158:161], v[184:187], v[34:37]
	v_mfma_f32_16x16x32_bf16 v[38:41], v[146:149], v[220:223], v[38:41]
	v_mfma_f32_16x16x32_bf16 v[38:41], v[150:153], v[224:227], v[38:41]
	v_mfma_f32_16x16x32_bf16 v[42:45], v[154:157], v[220:223], v[42:45]
	v_mfma_f32_16x16x32_bf16 v[42:45], v[158:161], v[224:227], v[42:45]
	s_barrier
; #define PG8_STAGE(bufoff, gbase, voff) do { _Pragma("unroll") for (int _i = 0; _i < 2; ++_i) \
;         __builtin_amdgcn_global_load_lds((const unsigned*)((const char*)(gbase) + (voff)[_i]), (PG8_LAS unsigned*)(lds + (bufoff) + ldsw + _i * 8192), 16, 0, 0); } while (0)
; #define PG8_LDA(dst, b, h) do { _Pragma("unroll") for (int m = 0; m < 4; ++m) _Pragma("unroll") for (int k = 0; k < 2; ++k) dst[m][k] = *(const PG8_LAS bf16x8*)(lds + PG8_SA(b, h) + aoff + m * 2048 + k * 1024); } while (0)
; #define PG8_LDB(dst, b, h) do { _Pragma("unroll") for (int n = 0; n < 2; ++n) _Pragma("unroll") for (int k = 0; k < 2; ++k) dst[n][k] = *(const PG8_LAS bf16x8*)(lds + PG8_SB(b, h) + boff + n * 2048 + k * 1024); } while (0)
; #define PG8_WAIT_V(n) asm volatile("s_waitcnt vmcnt(" #n ")" ::: "memory")
; #define PG8_WAIT_L(n) asm volatile("s_waitcnt lgkmcnt(" #n ")" ::: "memory")
; #define PG8_BAR __builtin_amdgcn_s_barrier()
; #define PG8_SCHED __builtin_amdgcn_sched_barrier(0)
;     ...
;             PG8_LDB(B0, 1, 0); PG8_LDB(B1, 1, 1); PG8_SCHED; PG8_LDA(At, 1, 0); PG8_STAGE(PG8_SA(0, 1), a2 + hstep, voffA);
;             PG8_WAIT_V(8); PG8_WAIT_L(0); PG8_BAR; PG8_MMA(0, 0, At, B0); PG8_MMA(0, 1, At, B1); PG8_BAR; PG8_SCHED;
;             PG8_LDA(At, 1, 1); PG8_STAGE(PG8_SB(1, 0), b3, voffB); PG8_STAGE(PG8_SB(1, 1), b3 + hstep, voffB); PG8_STAGE(PG8_SA(1, 0), a3, voffA);
;             PG8_WAIT_V(8); PG8_WAIT_L(0); PG8_BAR; PG8_MMA(1, 0, At, B0); PG8_MMA(1, 1, At, B1); PG8_BAR; PG8_SCHED;
	s_setprio 0
	s_add_i32 s19, 0, 0x18000
	s_add_i32 s51, 0, 0x1c000
	ds_read_b128 v[66:69], v200 offset:32768
	ds_read_b128 v[70:73], v200 offset:33792
	ds_read_b128 v[82:85], v200 offset:34816
	ds_read_b128 v[142:145], v200 offset:35840
	ds_read_b128 v[146:149], v200 offset:49152
	ds_read_b128 v[150:153], v200 offset:50176
	ds_read_b128 v[154:157], v200 offset:51200
	ds_read_b128 v[158:161], v200 offset:52224
	s_add_u32 s12, s40, 0x80000
	s_addc_u32 s13, s41, 0
	s_mov_b32 m0, s44
	ds_read_b128 v[162:165], v219 offset:32768
	ds_read_b128 v[166:169], v219 offset:33792
	ds_read_b128 v[170:173], v219 offset:34816
	ds_read_b128 v[174:177], v219 offset:35840
	ds_read_b128 v[178:181], v219 offset:36864
	ds_read_b128 v[184:187], v219 offset:37888
	ds_read_b128 v[220:223], v219 offset:38912
	ds_read_b128 v[224:227], v219 offset:39936
	global_load_lds_dwordx4 v188, s[12:13]
	s_mov_b32 m0, s46
	s_nop 0
	global_load_lds_dwordx4 v190, s[12:13]
	s_waitcnt vmcnt(8)
	s_waitcnt lgkmcnt(0)
	s_setprio 1
	s_barrier
	v_mfma_f32_16x16x32_bf16 v[114:117], v[66:69], v[162:165], v[114:117]
	v_mfma_f32_16x16x32_bf16 v[114:117], v[70:73], v[166:169], v[114:117]
	v_mfma_f32_16x16x32_bf16 v[106:109], v[82:85], v[162:165], v[106:109]
	v_mfma_f32_16x16x32_bf16 v[106:109], v[142:145], v[166:169], v[106:109]
	v_mfma_f32_16x16x32_bf16 v[110:113], v[66:69], v[170:173], v[110:113]
	v_mfma_f32_16x16x32_bf16 v[110:113], v[70:73], v[174:177], v[110:113]
	v_mfma_f32_16x16x32_bf16 v[102:105], v[82:85], v[170:173], v[102:105]
	v_mfma_f32_16x16x32_bf16 v[102:105], v[142:145], v[174:177], v[102:105]
	v_mfma_f32_16x16x32_bf16 v[78:81], v[66:69], v[178:181], v[78:81]
	v_mfma_f32_16x16x32_bf16 v[78:81], v[70:73], v[184:187], v[78:81]
	v_mfma_f32_16x16x32_bf16 v[138:141], v[82:85], v[178:181], v[138:141]
	v_mfma_f32_16x16x32_bf16 v[138:141], v[142:145], v[184:187], v[138:141]
	v_mfma_f32_16x16x32_bf16 v[74:77], v[66:69], v[220:223], v[74:77]
	v_mfma_f32_16x16x32_bf16 v[74:77], v[70:73], v[224:227], v[74:77]
	v_mfma_f32_16x16x32_bf16 v[134:137], v[82:85], v[220:223], v[134:137]
	v_mfma_f32_16x16x32_bf16 v[134:137], v[142:145], v[224:227], v[134:137]
	v_mfma_f32_16x16x32_bf16 v[98:101], v[146:149], v[162:165], v[98:101]
	v_mfma_f32_16x16x32_bf16 v[98:101], v[150:153], v[166:169], v[98:101]
	v_mfma_f32_16x16x32_bf16 v[90:93], v[154:157], v[162:165], v[90:93]
	v_mfma_f32_16x16x32_bf16 v[90:93], v[158:161], v[166:169], v[90:93]
	v_mfma_f32_16x16x32_bf16 v[94:97], v[146:149], v[170:173], v[94:97]
	v_mfma_f32_16x16x32_bf16 v[94:97], v[150:153], v[174:177], v[94:97]
	v_mfma_f32_16x16x32_bf16 v[86:89], v[154:157], v[170:173], v[86:89]
	v_mfma_f32_16x16x32_bf16 v[86:89], v[158:161], v[174:177], v[86:89]
	v_mfma_f32_16x16x32_bf16 v[130:133], v[146:149], v[178:181], v[130:133]
	v_mfma_f32_16x16x32_bf16 v[130:133], v[150:153], v[184:187], v[130:133]
	v_mfma_f32_16x16x32_bf16 v[122:125], v[154:157], v[178:181], v[122:125]
	v_mfma_f32_16x16x32_bf16 v[122:125], v[158:161], v[184:187], v[122:125]
	v_mfma_f32_16x16x32_bf16 v[126:129], v[146:149], v[220:223], v[126:129]
	v_mfma_f32_16x16x32_bf16 v[126:129], v[150:153], v[224:227], v[126:129]
	v_mfma_f32_16x16x32_bf16 v[118:121], v[154:157], v[220:223], v[118:121]
	v_mfma_f32_16x16x32_bf16 v[118:121], v[158:161], v[224:227], v[118:121]
	s_barrier
	s_setprio 0
	s_add_i32 s12, s19, s37
	s_mov_b32 m0, s12
	ds_read_b128 v[162:165], v219 offset:49152
	ds_read_b128 v[166:169], v219 offset:50176
	ds_read_b128 v[170:173], v219 offset:51200
	ds_read_b128 v[174:177], v219 offset:52224
	ds_read_b128 v[178:181], v219 offset:53248
	ds_read_b128 v[184:187], v219 offset:54272
	ds_read_b128 v[220:223], v219 offset:55296
	ds_read_b128 v[224:227], v219 offset:56320
	s_add_u32 s100, vcc_lo, 0x80
	s_addc_u32 s101, vcc_hi, 0
	global_load_lds_dwordx4 v182, s[100:101]
	s_add_i32 m0, s12, 0x2000
	s_add_u32 s12, vcc_lo, 0x80080
	s_addc_u32 s13, vcc_hi, 0
	s_add_i32 s19, s51, s37
	global_load_lds_dwordx4 v192, s[100:101]
	s_mov_b32 m0, s19
	s_nop 0
	global_load_lds_dwordx4 v182, s[12:13]
	s_add_i32 m0, s19, 0x2000
	s_nop 0
	global_load_lds_dwordx4 v192, s[12:13]
	s_mov_b32 m0, s45
	s_nop 0
	s_add_u32 s100, s40, 0x80
	s_addc_u32 s101, s41, 0
	global_load_lds_dwordx4 v188, s[100:101]
	s_mov_b32 m0, s24
	s_nop 0
	global_load_lds_dwordx4 v190, s[100:101]
	s_waitcnt vmcnt(8)
	s_waitcnt lgkmcnt(0)
	s_setprio 1
	s_barrier
	v_mfma_f32_16x16x32_bf16 v[30:33], v[66:69], v[162:165], v[30:33]
	v_mfma_f32_16x16x32_bf16 v[30:33], v[70:73], v[166:169], v[30:33]
	v_mfma_f32_16x16x32_bf16 v[22:25], v[82:85], v[162:165], v[22:25]
	v_mfma_f32_16x16x32_bf16 v[22:25], v[142:145], v[166:169], v[22:25]
	v_mfma_f32_16x16x32_bf16 v[26:29], v[66:69], v[170:173], v[26:29]
	v_mfma_f32_16x16x32_bf16 v[26:29], v[70:73], v[174:177], v[26:29]
	v_mfma_f32_16x16x32_bf16 v[18:21], v[82:85], v[170:173], v[18:21]
	v_mfma_f32_16x16x32_bf16 v[18:21], v[142:145], v[174:177], v[18:21]
	v_mfma_f32_16x16x32_bf16 v[62:65], v[66:69], v[178:181], v[62:65]
	v_mfma_f32_16x16x32_bf16 v[62:65], v[70:73], v[184:187], v[62:65]
	v_mfma_f32_16x16x32_bf16 v[54:57], v[82:85], v[178:181], v[54:57]
	v_mfma_f32_16x16x32_bf16 v[54:57], v[142:145], v[184:187], v[54:57]
	v_mfma_f32_16x16x32_bf16 v[58:61], v[66:69], v[220:223], v[58:61]
	v_mfma_f32_16x16x32_bf16 v[58:61], v[70:73], v[224:227], v[58:61]
	v_mfma_f32_16x16x32_bf16 v[50:53], v[82:85], v[220:223], v[50:53]
	v_mfma_f32_16x16x32_bf16 v[50:53], v[142:145], v[224:227], v[50:53]
	v_mfma_f32_16x16x32_bf16 v[14:17], v[146:149], v[162:165], v[14:17]
	v_mfma_f32_16x16x32_bf16 v[14:17], v[150:153], v[166:169], v[14:17]
	v_mfma_f32_16x16x32_bf16 v[6:9], v[154:157], v[162:165], v[6:9]
	v_mfma_f32_16x16x32_bf16 v[6:9], v[158:161], v[166:169], v[6:9]
	v_mfma_f32_16x16x32_bf16 v[10:13], v[146:149], v[170:173], v[10:13]
	v_mfma_f32_16x16x32_bf16 v[10:13], v[150:153], v[174:177], v[10:13]
	v_mfma_f32_16x16x32_bf16 v[2:5], v[154:157], v[170:173], v[2:5]
	v_mfma_f32_16x16x32_bf16 v[2:5], v[158:161], v[174:177], v[2:5]
	v_mfma_f32_16x16x32_bf16 v[46:49], v[146:149], v[178:181], v[46:49]
	v_mfma_f32_16x16x32_bf16 v[46:49], v[150:153], v[184:187], v[46:49]
	v_mfma_f32_16x16x32_bf16 v[34:37], v[154:157], v[178:181], v[34:37]
	v_mfma_f32_16x16x32_bf16 v[34:37], v[158:161], v[184:187], v[34:37]
	v_mfma_f32_16x16x32_bf16 v[38:41], v[146:149], v[220:223], v[38:41]
	v_mfma_f32_16x16x32_bf16 v[38:41], v[150:153], v[224:227], v[38:41]
	v_mfma_f32_16x16x32_bf16 v[42:45], v[154:157], v[220:223], v[42:45]
	v_mfma_f32_16x16x32_bf16 v[42:45], v[158:161], v[224:227], v[42:45]
	s_barrier
	s_setprio 0
	s_add_i32 s0, s0, 2
	s_add_u32 s66, s66, 0x100
	s_addc_u32 s67, s67, 0
	s_cmp_gt_u32 s0, 29
	s_mov_b64 s[12:13], s[96:97]
	s_cbranch_scc0 .LBB0_1327
	s_and_b64 vcc, exec, s[78:79]
	s_cbranch_vccz .LBB0_1330
	s_barrier

; #define PG8_STAGE(bufoff, gbase, voff) do { _Pragma("unroll") for (int _i = 0; _i < 2; ++_i) \
;         __builtin_amdgcn_global_load_lds((const unsigned*)((const char*)(gbase) + (voff)[_i]), (PG8_LAS unsigned*)(lds + (bufoff) + ldsw + _i * 8192), 16, 0, 0); } while (0)
; #define PG8_LDA(dst, b, h) do { _Pragma("unroll") for (int m = 0; m < 4; ++m) _Pragma("unroll") for (int k = 0; k < 2; ++k) dst[m][k] = *(const PG8_LAS bf16x8*)(lds + PG8_SA(b, h) + aoff + m * 2048 + k * 1024); } while (0)
; #define PG8_LDB(dst, b, h) do { _Pragma("unroll") for (int n = 0; n < 2; ++n) _Pragma("unroll") for (int k = 0; k < 2; ++k) dst[n][k] = *(const PG8_LAS bf16x8*)(lds + PG8_SB(b, h) + boff + n * 2048 + k * 1024); } while (0)
; #define PG8_WAIT_L(n) asm volatile("s_waitcnt lgkmcnt(" #n ")" ::: "memory")
; #define PG8_WAIT_V_SEL(sel) asm volatile("s_cmp_eq_u32 %0, 0\n\ts_cbranch_scc1 .Lw8_%=\n\ts_waitcnt vmcnt(22)\n\ts_branch .Lwd_%=\n.Lw8_%=:\n\ts_waitcnt vmcnt(8)\n.Lwd_%=:" :: "s"(sel) : "memory", "scc")
; #define PG8_BAR __builtin_amdgcn_s_barrier()
; #define PG8_SCHED __builtin_amdgcn_sched_barrier(0)
;     ...
;             const bool last = (t == nt * KREP - 2);
;             const int t1w = KREP > 1 ? ((t + 1) & (nt - 1)) : t + 1, t2w = KREP > 1 ? ((t + 2) & (nt - 1)) : t + 2;
;             const char* a1 = cA + (size_t)t1w * kstep;
;             const char* a2 = last ? nA : cA + (size_t)t2w * kstep; const char* b2 = last ? nB : cB + (size_t)t2w * kstep;
;             const char* a3 = a2 + kstep; const char* b3 = b2 + kstep;
;             if (last && has_next) S.a_ready(nxt);
;             const int relax = __builtin_amdgcn_readfirstlane((MK_RELAXW && t == 0 && ui > 0) ? 1 : 0);
;             if constexpr (SP2) {
;             PG8_LDB(B0, 0, 0); PG8_LDB(B1, 0, 1); PG8_SCHED; PG8_LDA(At, 0, 0); PG8_STAGE(PG8_SA(1, 1), a1 + hstep, voffA);
;             PG8_WAIT_V_SEL(relax);
;             PG8_WAIT_L(0); PG8_BAR; PG8_MMA(0, 0, At, B0); PG8_MMA(0, 1, At, B1); PG8_BAR; PG8_SCHED;
;             PG8_LDA(At, 0, 1); PG8_STAGE(PG8_SB(0, 0), b2, voffB); PG8_STAGE(PG8_SB(0, 1), b2 + hstep, voffB); PG8_STAGE(PG8_SA(0, 0), a2, voffA);
;             PG8_WAIT_V_SEL(relax);
;             PG8_WAIT_L(0); PG8_BAR; PG8_MMA(1, 0, At, B0); PG8_MMA(1, 1, At, B1); PG8_BAR; PG8_SCHED;
.LBB0_1648:
	s_add_u32 s10, s8, 0x100
	s_addc_u32 s11, s9, 0
	s_add_i32 s46, 0, 0x10000
	s_cmpk_eq_i32 s45, 0x52
	s_cselect_b32 s41, s1, s11
	s_cselect_b32 s40, s0, s10
	s_cselect_b32 s81, s79, s44
	s_cselect_b32 s80, s78, s37
	s_add_i32 s47, 0, 0x14000
	ds_read_b128 v[58:61], v206
	ds_read_b128 v[62:65], v206 offset:1024
	ds_read_b128 v[74:77], v206 offset:2048
	ds_read_b128 v[78:81], v206 offset:3072
	ds_read_b128 v[130:133], v206 offset:16384
	ds_read_b128 v[142:145], v206 offset:17408
	ds_read_b128 v[154:157], v206 offset:18432
	ds_read_b128 v[158:161], v206 offset:19456
	s_add_i32 m0, s91, 0xc000
	ds_read_b128 v[162:165], v246
	ds_read_b128 v[166:169], v246 offset:1024
	ds_read_b128 v[170:173], v246 offset:2048
	ds_read_b128 v[174:177], v246 offset:3072
	ds_read_b128 v[184:187], v246 offset:4096
	ds_read_b128 v[194:197], v246 offset:5120
	ds_read_b128 v[198:201], v246 offset:6144
	ds_read_b128 v[202:205], v246 offset:7168
	global_load_lds_dwordx4 v190, s[8:9]
	s_add_i32 m0, s91, 0xe000
	s_nop 0
	global_load_lds_dwordx4 v192, s[8:9]
	s_waitcnt vmcnt(8)
	s_waitcnt lgkmcnt(0)
	s_setprio 1
	s_barrier
	v_mfma_f32_16x16x32_bf16 v[150:153], v[58:61], v[162:165], v[150:153]
	v_mfma_f32_16x16x32_bf16 v[150:153], v[62:65], v[166:169], v[150:153]
	v_mfma_f32_16x16x32_bf16 v[146:149], v[74:77], v[162:165], v[146:149]
	v_mfma_f32_16x16x32_bf16 v[146:149], v[78:81], v[166:169], v[146:149]
	v_mfma_f32_16x16x32_bf16 v[126:129], v[58:61], v[170:173], v[126:129]
	v_mfma_f32_16x16x32_bf16 v[126:129], v[62:65], v[174:177], v[126:129]
	v_mfma_f32_16x16x32_bf16 v[122:125], v[74:77], v[170:173], v[122:125]
	v_mfma_f32_16x16x32_bf16 v[122:125], v[78:81], v[174:177], v[122:125]
	v_mfma_f32_16x16x32_bf16 v[110:113], v[58:61], v[184:187], v[110:113]
	v_mfma_f32_16x16x32_bf16 v[110:113], v[62:65], v[194:197], v[110:113]
	v_mfma_f32_16x16x32_bf16 v[106:109], v[74:77], v[184:187], v[106:109]
	v_mfma_f32_16x16x32_bf16 v[106:109], v[78:81], v[194:197], v[106:109]
	v_mfma_f32_16x16x32_bf16 v[94:97], v[58:61], v[198:201], v[94:97]
	v_mfma_f32_16x16x32_bf16 v[94:97], v[62:65], v[202:205], v[94:97]
	v_mfma_f32_16x16x32_bf16 v[90:93], v[74:77], v[198:201], v[90:93]
	v_mfma_f32_16x16x32_bf16 v[90:93], v[78:81], v[202:205], v[90:93]
	v_mfma_f32_16x16x32_bf16 v[138:141], v[130:133], v[162:165], v[138:141]
	v_mfma_f32_16x16x32_bf16 v[138:141], v[142:145], v[166:169], v[138:141]
	v_mfma_f32_16x16x32_bf16 v[134:137], v[154:157], v[162:165], v[134:137]
	v_mfma_f32_16x16x32_bf16 v[134:137], v[158:161], v[166:169], v[134:137]
	v_mfma_f32_16x16x32_bf16 v[118:121], v[130:133], v[170:173], v[118:121]
	v_mfma_f32_16x16x32_bf16 v[118:121], v[142:145], v[174:177], v[118:121]
	v_mfma_f32_16x16x32_bf16 v[114:117], v[154:157], v[170:173], v[114:117]
	v_mfma_f32_16x16x32_bf16 v[114:117], v[158:161], v[174:177], v[114:117]
	v_mfma_f32_16x16x32_bf16 v[102:105], v[130:133], v[184:187], v[102:105]
	v_mfma_f32_16x16x32_bf16 v[102:105], v[142:145], v[194:197], v[102:105]
	v_mfma_f32_16x16x32_bf16 v[98:101], v[154:157], v[184:187], v[98:101]
	v_mfma_f32_16x16x32_bf16 v[98:101], v[158:161], v[194:197], v[98:101]
	v_mfma_f32_16x16x32_bf16 v[86:89], v[130:133], v[198:201], v[86:89]
	v_mfma_f32_16x16x32_bf16 v[86:89], v[142:145], v[202:205], v[86:89]
	v_mfma_f32_16x16x32_bf16 v[82:85], v[154:157], v[198:201], v[82:85]
	v_mfma_f32_16x16x32_bf16 v[82:85], v[158:161], v[202:205], v[82:85]
	s_barrier
	s_setprio 0
	s_add_i32 s8, s46, s90
	s_mov_b32 m0, s8
	ds_read_b128 v[162:165], v246 offset:16384
	ds_read_b128 v[166:169], v246 offset:17408
	ds_read_b128 v[170:173], v246 offset:18432
	ds_read_b128 v[174:177], v246 offset:19456
	ds_read_b128 v[184:187], v246 offset:20480
	ds_read_b128 v[194:197], v246 offset:21504
	ds_read_b128 v[198:201], v246 offset:22528
	ds_read_b128 v[202:205], v246 offset:23552
	global_load_lds_dwordx4 v182, s[80:81]
	s_add_i32 m0, s8, 0x2000
	s_add_u32 s8, s80, 0x158000
	s_addc_u32 s9, s81, 0
	s_add_i32 s46, s47, s90
	global_load_lds_dwordx4 v188, s[80:81]
	s_mov_b32 m0, s46
	s_nop 0
	global_load_lds_dwordx4 v182, s[8:9]
	s_add_i32 m0, s46, 0x2000
	s_nop 0
	global_load_lds_dwordx4 v188, s[8:9]
	s_mov_b32 m0, s91
	s_nop 0
	global_load_lds_dwordx4 v178, s[40:41]
	s_mov_b32 m0, s92
	s_nop 0
	global_load_lds_dwordx4 v180, s[40:41]
	s_waitcnt vmcnt(8)
	s_waitcnt lgkmcnt(0)
	s_setprio 1
	s_barrier
	v_mfma_f32_16x16x32_bf16 v[70:73], v[58:61], v[162:165], v[70:73]
	v_mfma_f32_16x16x32_bf16 v[70:73], v[62:65], v[166:169], v[70:73]
	v_mfma_f32_16x16x32_bf16 v[66:69], v[74:77], v[162:165], v[66:69]
	v_mfma_f32_16x16x32_bf16 v[66:69], v[78:81], v[166:169], v[66:69]
	v_mfma_f32_16x16x32_bf16 v[46:49], v[58:61], v[170:173], v[46:49]
	v_mfma_f32_16x16x32_bf16 v[46:49], v[62:65], v[174:177], v[46:49]
	v_mfma_f32_16x16x32_bf16 v[42:45], v[74:77], v[170:173], v[42:45]
	v_mfma_f32_16x16x32_bf16 v[42:45], v[78:81], v[174:177], v[42:45]
	v_mfma_f32_16x16x32_bf16 v[30:33], v[58:61], v[184:187], v[30:33]
	v_mfma_f32_16x16x32_bf16 v[30:33], v[62:65], v[194:197], v[30:33]
	v_mfma_f32_16x16x32_bf16 v[26:29], v[74:77], v[184:187], v[26:29]
	v_mfma_f32_16x16x32_bf16 v[26:29], v[78:81], v[194:197], v[26:29]
	v_mfma_f32_16x16x32_bf16 v[14:17], v[58:61], v[198:201], v[14:17]
	v_mfma_f32_16x16x32_bf16 v[14:17], v[62:65], v[202:205], v[14:17]
	v_mfma_f32_16x16x32_bf16 v[10:13], v[74:77], v[198:201], v[10:13]
	v_mfma_f32_16x16x32_bf16 v[10:13], v[78:81], v[202:205], v[10:13]
	v_mfma_f32_16x16x32_bf16 v[54:57], v[130:133], v[162:165], v[54:57]
	v_mfma_f32_16x16x32_bf16 v[54:57], v[142:145], v[166:169], v[54:57]
	v_mfma_f32_16x16x32_bf16 v[50:53], v[154:157], v[162:165], v[50:53]
	v_mfma_f32_16x16x32_bf16 v[50:53], v[158:161], v[166:169], v[50:53]
	v_mfma_f32_16x16x32_bf16 v[38:41], v[130:133], v[170:173], v[38:41]
	v_mfma_f32_16x16x32_bf16 v[38:41], v[142:145], v[174:177], v[38:41]
	v_mfma_f32_16x16x32_bf16 v[34:37], v[154:157], v[170:173], v[34:37]
	v_mfma_f32_16x16x32_bf16 v[34:37], v[158:161], v[174:177], v[34:37]
	v_mfma_f32_16x16x32_bf16 v[22:25], v[130:133], v[184:187], v[22:25]
	v_mfma_f32_16x16x32_bf16 v[22:25], v[142:145], v[194:197], v[22:25]
	v_mfma_f32_16x16x32_bf16 v[18:21], v[154:157], v[184:187], v[18:21]
	v_mfma_f32_16x16x32_bf16 v[18:21], v[158:161], v[194:197], v[18:21]
	v_mfma_f32_16x16x32_bf16 v[6:9], v[130:133], v[198:201], v[6:9]
	v_mfma_f32_16x16x32_bf16 v[6:9], v[142:145], v[202:205], v[6:9]
	v_mfma_f32_16x16x32_bf16 v[2:5], v[154:157], v[198:201], v[2:5]
	v_mfma_f32_16x16x32_bf16 v[2:5], v[158:161], v[202:205], v[2:5]
	s_barrier
; #define PG8_STAGE(bufoff, gbase, voff) do { _Pragma("unroll") for (int _i = 0; _i < 2; ++_i) \
;         __builtin_amdgcn_global_load_lds((const unsigned*)((const char*)(gbase) + (voff)[_i]), (PG8_LAS unsigned*)(lds + (bufoff) + ldsw + _i * 8192), 16, 0, 0); } while (0)
; #define PG8_LDA(dst, b, h) do { _Pragma("unroll") for (int m = 0; m < 4; ++m) _Pragma("unroll") for (int k = 0; k < 2; ++k) dst[m][k] = *(const PG8_LAS bf16x8*)(lds + PG8_SA(b, h) + aoff + m * 2048 + k * 1024); } while (0)
; #define PG8_LDB(dst, b, h) do { _Pragma("unroll") for (int n = 0; n < 2; ++n) _Pragma("unroll") for (int k = 0; k < 2; ++k) dst[n][k] = *(const PG8_LAS bf16x8*)(lds + PG8_SB(b, h) + boff + n * 2048 + k * 1024); } while (0)
; #define PG8_WAIT_V(n) asm volatile("s_waitcnt vmcnt(" #n ")" ::: "memory")
; #define PG8_WAIT_L(n) asm volatile("s_waitcnt lgkmcnt(" #n ")" ::: "memory")
; #define PG8_BAR __builtin_amdgcn_s_barrier()
; #define PG8_SCHED __builtin_amdgcn_sched_barrier(0)
;     ...
;             PG8_LDB(B0, 1, 0); PG8_LDB(B1, 1, 1); PG8_SCHED; PG8_LDA(At, 1, 0); PG8_STAGE(PG8_SA(0, 1), a2 + hstep, voffA);
;             PG8_WAIT_V(8); PG8_WAIT_L(0); PG8_BAR; PG8_MMA(0, 0, At, B0); PG8_MMA(0, 1, At, B1); PG8_BAR; PG8_SCHED;
;             PG8_LDA(At, 1, 1); PG8_STAGE(PG8_SB(1, 0), b3, voffB); PG8_STAGE(PG8_SB(1, 1), b3 + hstep, voffB); PG8_STAGE(PG8_SA(1, 0), a3, voffA);
;             PG8_WAIT_V(8); PG8_WAIT_L(0); PG8_BAR; PG8_MMA(1, 0, At, B0); PG8_MMA(1, 1, At, B1); PG8_BAR; PG8_SCHED;
	s_setprio 0
	s_add_i32 s46, 0, 0x18000
	s_add_i32 s47, 0, 0x1c000
	ds_read_b128 v[58:61], v206 offset:32768
	ds_read_b128 v[62:65], v206 offset:33792
	ds_read_b128 v[74:77], v206 offset:34816
	ds_read_b128 v[78:81], v206 offset:35840
	ds_read_b128 v[130:133], v206 offset:49152
	ds_read_b128 v[142:145], v206 offset:50176
	ds_read_b128 v[154:157], v206 offset:51200
	ds_read_b128 v[158:161], v206 offset:52224
	s_add_u32 s8, s40, 0x158000
	s_addc_u32 s9, s41, 0
	s_mov_b32 m0, s93
	ds_read_b128 v[162:165], v246 offset:32768
	ds_read_b128 v[166:169], v246 offset:33792
	ds_read_b128 v[170:173], v246 offset:34816
	ds_read_b128 v[174:177], v246 offset:35840
	ds_read_b128 v[184:187], v246 offset:36864
	ds_read_b128 v[194:197], v246 offset:37888
	ds_read_b128 v[198:201], v246 offset:38912
	ds_read_b128 v[202:205], v246 offset:39936
	global_load_lds_dwordx4 v178, s[8:9]
	s_mov_b32 m0, s94
	s_nop 0
	global_load_lds_dwordx4 v180, s[8:9]
	s_waitcnt vmcnt(8)
	s_waitcnt lgkmcnt(0)
	s_setprio 1
	s_barrier
	v_mfma_f32_16x16x32_bf16 v[150:153], v[58:61], v[162:165], v[150:153]
	v_mfma_f32_16x16x32_bf16 v[150:153], v[62:65], v[166:169], v[150:153]
	v_mfma_f32_16x16x32_bf16 v[146:149], v[74:77], v[162:165], v[146:149]
	v_mfma_f32_16x16x32_bf16 v[146:149], v[78:81], v[166:169], v[146:149]
	v_mfma_f32_16x16x32_bf16 v[126:129], v[58:61], v[170:173], v[126:129]
	v_mfma_f32_16x16x32_bf16 v[126:129], v[62:65], v[174:177], v[126:129]
	v_mfma_f32_16x16x32_bf16 v[122:125], v[74:77], v[170:173], v[122:125]
	v_mfma_f32_16x16x32_bf16 v[122:125], v[78:81], v[174:177], v[122:125]
	v_mfma_f32_16x16x32_bf16 v[110:113], v[58:61], v[184:187], v[110:113]
	v_mfma_f32_16x16x32_bf16 v[110:113], v[62:65], v[194:197], v[110:113]
	v_mfma_f32_16x16x32_bf16 v[106:109], v[74:77], v[184:187], v[106:109]
	v_mfma_f32_16x16x32_bf16 v[106:109], v[78:81], v[194:197], v[106:109]
	v_mfma_f32_16x16x32_bf16 v[94:97], v[58:61], v[198:201], v[94:97]
	v_mfma_f32_16x16x32_bf16 v[94:97], v[62:65], v[202:205], v[94:97]
	v_mfma_f32_16x16x32_bf16 v[90:93], v[74:77], v[198:201], v[90:93]
	v_mfma_f32_16x16x32_bf16 v[90:93], v[78:81], v[202:205], v[90:93]
	v_mfma_f32_16x16x32_bf16 v[138:141], v[130:133], v[162:165], v[138:141]
	v_mfma_f32_16x16x32_bf16 v[138:141], v[142:145], v[166:169], v[138:141]
	v_mfma_f32_16x16x32_bf16 v[134:137], v[154:157], v[162:165], v[134:137]
	v_mfma_f32_16x16x32_bf16 v[134:137], v[158:161], v[166:169], v[134:137]
	v_mfma_f32_16x16x32_bf16 v[118:121], v[130:133], v[170:173], v[118:121]
	v_mfma_f32_16x16x32_bf16 v[118:121], v[142:145], v[174:177], v[118:121]
	v_mfma_f32_16x16x32_bf16 v[114:117], v[154:157], v[170:173], v[114:117]
	v_mfma_f32_16x16x32_bf16 v[114:117], v[158:161], v[174:177], v[114:117]
	v_mfma_f32_16x16x32_bf16 v[102:105], v[130:133], v[184:187], v[102:105]
	v_mfma_f32_16x16x32_bf16 v[102:105], v[142:145], v[194:197], v[102:105]
	v_mfma_f32_16x16x32_bf16 v[98:101], v[154:157], v[184:187], v[98:101]
	v_mfma_f32_16x16x32_bf16 v[98:101], v[158:161], v[194:197], v[98:101]
	v_mfma_f32_16x16x32_bf16 v[86:89], v[130:133], v[198:201], v[86:89]
	v_mfma_f32_16x16x32_bf16 v[86:89], v[142:145], v[202:205], v[86:89]
	v_mfma_f32_16x16x32_bf16 v[82:85], v[154:157], v[198:201], v[82:85]
	v_mfma_f32_16x16x32_bf16 v[82:85], v[158:161], v[202:205], v[82:85]
	s_barrier
	s_setprio 0
	s_add_i32 s8, s46, s90
	s_mov_b32 m0, s8
	ds_read_b128 v[162:165], v246 offset:49152
	ds_read_b128 v[166:169], v246 offset:50176
	ds_read_b128 v[170:173], v246 offset:51200
	ds_read_b128 v[174:177], v246 offset:52224
	ds_read_b128 v[184:187], v246 offset:53248
	ds_read_b128 v[194:197], v246 offset:54272
	ds_read_b128 v[198:201], v246 offset:55296
	ds_read_b128 v[202:205], v246 offset:56320
	s_add_u32 s100, s80, 0x80
	s_addc_u32 s101, s81, 0
	global_load_lds_dwordx4 v182, s[100:101]
	s_add_i32 m0, s8, 0x2000
	s_add_u32 s8, s80, 0x158080
	s_addc_u32 s9, s81, 0
	s_add_i32 vcc_lo, s47, s90
	global_load_lds_dwordx4 v188, s[100:101]
	s_mov_b32 m0, vcc_lo
	s_nop 0
	global_load_lds_dwordx4 v182, s[8:9]
	s_add_i32 m0, vcc_lo, 0x2000
	s_nop 0
	global_load_lds_dwordx4 v188, s[8:9]
	s_mov_b32 m0, s31
	s_nop 0
	s_add_u32 s100, s40, 0x80
	s_addc_u32 s101, s41, 0
	global_load_lds_dwordx4 v178, s[100:101]
	s_mov_b32 m0, s56
	s_nop 0
	global_load_lds_dwordx4 v180, s[100:101]
	s_waitcnt vmcnt(8)
	s_waitcnt lgkmcnt(0)
	s_setprio 1
	s_barrier
	v_mfma_f32_16x16x32_bf16 v[70:73], v[58:61], v[162:165], v[70:73]
	v_mfma_f32_16x16x32_bf16 v[70:73], v[62:65], v[166:169], v[70:73]
	v_mfma_f32_16x16x32_bf16 v[66:69], v[74:77], v[162:165], v[66:69]
	v_mfma_f32_16x16x32_bf16 v[66:69], v[78:81], v[166:169], v[66:69]
	v_mfma_f32_16x16x32_bf16 v[46:49], v[58:61], v[170:173], v[46:49]
	v_mfma_f32_16x16x32_bf16 v[46:49], v[62:65], v[174:177], v[46:49]
	v_mfma_f32_16x16x32_bf16 v[42:45], v[74:77], v[170:173], v[42:45]
	v_mfma_f32_16x16x32_bf16 v[42:45], v[78:81], v[174:177], v[42:45]
	v_mfma_f32_16x16x32_bf16 v[30:33], v[58:61], v[184:187], v[30:33]
	v_mfma_f32_16x16x32_bf16 v[30:33], v[62:65], v[194:197], v[30:33]
	v_mfma_f32_16x16x32_bf16 v[26:29], v[74:77], v[184:187], v[26:29]
	v_mfma_f32_16x16x32_bf16 v[26:29], v[78:81], v[194:197], v[26:29]
	v_mfma_f32_16x16x32_bf16 v[14:17], v[58:61], v[198:201], v[14:17]
	v_mfma_f32_16x16x32_bf16 v[14:17], v[62:65], v[202:205], v[14:17]
	v_mfma_f32_16x16x32_bf16 v[10:13], v[74:77], v[198:201], v[10:13]
	v_mfma_f32_16x16x32_bf16 v[10:13], v[78:81], v[202:205], v[10:13]
	v_mfma_f32_16x16x32_bf16 v[54:57], v[130:133], v[162:165], v[54:57]
	v_mfma_f32_16x16x32_bf16 v[54:57], v[142:145], v[166:169], v[54:57]
	v_mfma_f32_16x16x32_bf16 v[50:53], v[154:157], v[162:165], v[50:53]
	v_mfma_f32_16x16x32_bf16 v[50:53], v[158:161], v[166:169], v[50:53]
	v_mfma_f32_16x16x32_bf16 v[38:41], v[130:133], v[170:173], v[38:41]
	v_mfma_f32_16x16x32_bf16 v[38:41], v[142:145], v[174:177], v[38:41]
	v_mfma_f32_16x16x32_bf16 v[34:37], v[154:157], v[170:173], v[34:37]
	v_mfma_f32_16x16x32_bf16 v[34:37], v[158:161], v[174:177], v[34:37]
	v_mfma_f32_16x16x32_bf16 v[22:25], v[130:133], v[184:187], v[22:25]
	v_mfma_f32_16x16x32_bf16 v[22:25], v[142:145], v[194:197], v[22:25]
	v_mfma_f32_16x16x32_bf16 v[18:21], v[154:157], v[184:187], v[18:21]
	v_mfma_f32_16x16x32_bf16 v[18:21], v[158:161], v[194:197], v[18:21]
	v_mfma_f32_16x16x32_bf16 v[6:9], v[130:133], v[198:201], v[6:9]
	v_mfma_f32_16x16x32_bf16 v[6:9], v[142:145], v[202:205], v[6:9]
	v_mfma_f32_16x16x32_bf16 v[2:5], v[154:157], v[198:201], v[2:5]
	v_mfma_f32_16x16x32_bf16 v[2:5], v[158:161], v[202:205], v[2:5]
	s_barrier
	s_setprio 0
	s_add_i32 s45, s45, 2
	s_add_u32 s37, s37, 0x100
	s_addc_u32 s44, s44, 0
	s_cmpk_gt_u32 s45, 0x53
	s_mov_b64 s[8:9], s[10:11]
	s_cbranch_scc0 .LBB0_1648
	s_and_b64 vcc, exec, s[76:77]
	s_cbranch_vccz .LBB0_1651
	s_barrier
